# merge: role-split workgroup - waves 4-7 stream the K-tiles (global->regs->LDS), waves 0-3 do all MFMAs with 64x64 wave tiles (one matrix wave per SIMD, a third fewer LDS fragment reads)
# baseline (speedup 1.0000x reference)
; DI f32x16 mfma(bf16x8 a, bf16x8 b, f32x16 c) { return __builtin_amdgcn_mfma_f32_32x32x16_bf16(a, b, c, 0, 0, 0); }
; DI f32x16 zero16() { f32x16 z; for (int i = 0; i < 16; ++i) z[i] = 0.f; return z; }
; DI int tidx() { int t = threadIdx.x; asm volatile("" : "+v"(t)); return t; }
; #define TASK_LOOP(t, nt, base) for (int t = (int)((blockIdx.x + gridDim.x - ((unsigned)(base) % gridDim.x)) % gridDim.x); t < (nt); t += gridDim.x)
; template <bool RFA, bool RFB, class LA, class LB, class EPI>
; DI void gemm_tile2s(u16* smem, int nk, LA la, LB lb, EPI epi) {
;     ...
;   auto compute = [&](int buf) __attribute__((always_inline)) {
;     const u16* Ab = As + buf * TILE_ELEMS + (wm * 64 + lr) * LDT + lh * 8;
;     const u16* Bb = Bs + buf * TILE_ELEMS + (wn * 32 + lr) * LDT + lh * 8;
; #pragma unroll
;     for (int ks = 0; ks < 4; ++ks) {
;       const bf16x8 a0 = *(const bf16x8*)(Ab + ks * 16);
;       const bf16x8 a1 = *(const bf16x8*)(Ab + 32 * LDT + ks * 16);
;       const bf16x8 b = *(const bf16x8*)(Bb + ks * 16);
;       acc[0] = mfma(a0, b, acc[0]);
;       acc[1] = mfma(a1, b, acc[1]);
;     }
;   };
; DI void phase_merge(const Prm& p, u16* smem, int l, int& base) {
;   TASK_LOOP(t, 8 * 128, base) {
;     const int tn = t & 7, tm = t >> 3, n0 = tn * 128, m0 = tm * 128;
;     f32x16 macc[2];
;     macc[0] = zero16(); macc[1] = zero16();
;     merge_branch(p, smem, p.PaT + (size_t)l * 1024 * 768, p.UT, 768, 0, n0, m0, macc);
;     merge_branch(p, smem, p.PbT + (size_t)l * 1024 * 128, p.ob, 128, 1, n0, m0, macc);
;     ...
;     merge_branch(p, smem, p.PdT + (size_t)l * 1024 * 256, p.od, 256, 3, n0, m0, macc);
;     const int tid2 = tidx(), lane = tid2 & 63, wave = tid2 >> 6, wm = wave >> 2, wn = wave & 3, lr = lane & 31, lh = lane >> 5;
;     const int tok = m0 + wn * 32 + lr;
.LBB0_2250:
	v_cmp_lt_u32_e32 vcc, 0xff, v224
	s_nop 4
	s_cbranch_vccnz .Lmrg_prod
	v_readlane_b32 s42, v252, 6
	v_readlane_b32 s43, v252, 7
	v_readlane_b32 s48, v253, 20
	v_readlane_b32 s49, v253, 21
	v_lshrrev_b32_e32 v226, 1, v224
	v_and_b32_e32 v227, 16, v226
	v_and_b32_e32 v228, 31, v224
	v_lshrrev_b32_e32 v229, 1, v224
	v_and_b32_e32 v229, 64, v229
	v_and_b32_e32 v226, 64, v224
	v_or_b32_e32 v226, v226, v228
	v_or_b32_e32 v228, v229, v228
	s_movk_i32 s52, 0x90
	v_mad_u32_u24 v234, v228, s52, v227
	v_mad_u32_u24 v235, v226, s52, v227
	v_add_u32_e32 v235, 0xd800, v235
	v_or_b32_e32 v229, v229, v227
	v_lshlrev_b32_e32 v229, 1, v229
	v_lshl_add_u32 v236, v226, 13, v229
	v_lshl_add_u32 v237, v226, 11, v229
	s_and_b32 s58, s31, 7
	s_lshl_b32 s58, s58, 7
	s_lshr_b32 s59, s31, 3
	s_lshl_b32 s59, s59, 7
	s_barrier
	ds_read_b128 v[130:133], v234
	ds_read_b128 v[138:141], v235
	ds_read_b128 v[134:137], v234 offset:4608
	ds_read_b128 v[142:145], v235 offset:4608
	ds_read_b128 v[146:149], v234 offset:32
	ds_read_b128 v[154:157], v235 offset:32
	ds_read_b128 v[150:153], v234 offset:4640
	ds_read_b128 v[158:161], v235 offset:4640
	s_waitcnt lgkmcnt(0)
.Lmrgc_task:
	s_lshl_b32 s52, s59, 13
	s_lshl_b32 s53, s58, 1
	s_add_u32 s52, s52, s53
	s_add_u32 s8, s42, s52
	s_addc_u32 s9, s43, 0
	s_add_u32 s10, s8, 0x1000
	s_addc_u32 s11, s9, 0
	s_lshl_b32 s52, s59, 11
	s_add_u32 s52, s52, s53
	s_add_u32 s12, s48, s52
	s_addc_u32 s13, s49, 0
	v_add_u32_e32 v244, 0x40000, v236
	global_load_dwordx4 v[194:197], v236, s[8:9]
	global_load_dwordx4 v[198:201], v236, s[8:9] offset:16
	global_load_dwordx4 v[202:205], v236, s[8:9] offset:64
	global_load_dwordx4 v[206:209], v236, s[8:9] offset:80
	global_load_dwordx4 v[210:213], v244, s[8:9]
	global_load_dwordx4 v[214:217], v244, s[8:9] offset:16
	global_load_dwordx4 v[218:221], v244, s[8:9] offset:64
	global_load_dwordx4 v[226:229], v244, s[8:9] offset:80
	ds_read_b128 v[162:165], v234 offset:64
	ds_read_b128 v[170:173], v235 offset:64
	s_waitcnt lgkmcnt(8)
	v_mfma_f32_32x32x16_bf16 v[2:17], v[130:133], v[138:141], 0
	ds_read_b128 v[166:169], v234 offset:4672
	ds_read_b128 v[174:177], v235 offset:4672
	s_waitcnt lgkmcnt(9)
	v_mfma_f32_32x32x16_bf16 v[18:33], v[134:137], v[138:141], 0
	ds_read_b128 v[178:181], v234 offset:96
	ds_read_b128 v[186:189], v235 offset:96
	s_waitcnt lgkmcnt(10)
	v_mfma_f32_32x32x16_bf16 v[34:49], v[130:133], v[142:145], 0
	ds_read_b128 v[182:185], v234 offset:4704
	ds_read_b128 v[190:193], v235 offset:4704
	v_mfma_f32_32x32x16_bf16 v[50:65], v[134:137], v[142:145], 0
	s_waitcnt lgkmcnt(10)
	v_mfma_f32_32x32x16_bf16 v[2:17], v[146:149], v[154:157], v[2:17]
	s_waitcnt lgkmcnt(9)
	v_mfma_f32_32x32x16_bf16 v[18:33], v[150:153], v[154:157], v[18:33]
	s_waitcnt lgkmcnt(8)
	v_mfma_f32_32x32x16_bf16 v[34:49], v[146:149], v[158:161], v[34:49]
	v_mfma_f32_32x32x16_bf16 v[50:65], v[150:153], v[158:161], v[50:65]
	ds_read_b128 v[130:133], v234 offset:18432
	ds_read_b128 v[138:141], v235 offset:18432
	s_waitcnt lgkmcnt(8)
	v_mfma_f32_32x32x16_bf16 v[2:17], v[162:165], v[170:173], v[2:17]
	ds_read_b128 v[134:137], v234 offset:23040
	ds_read_b128 v[142:145], v235 offset:23040
	s_waitcnt lgkmcnt(9)
	v_mfma_f32_32x32x16_bf16 v[18:33], v[166:169], v[170:173], v[18:33]
	ds_read_b128 v[146:149], v234 offset:18464
	ds_read_b128 v[154:157], v235 offset:18464
	s_waitcnt lgkmcnt(10)
	v_mfma_f32_32x32x16_bf16 v[34:49], v[162:165], v[174:177], v[34:49]
	ds_read_b128 v[150:153], v234 offset:23072
	ds_read_b128 v[158:161], v235 offset:23072
	v_mfma_f32_32x32x16_bf16 v[50:65], v[166:169], v[174:177], v[50:65]
	s_waitcnt lgkmcnt(10)
	v_mfma_f32_32x32x16_bf16 v[2:17], v[178:181], v[186:189], v[2:17]
	s_waitcnt lgkmcnt(9)
	v_mfma_f32_32x32x16_bf16 v[18:33], v[182:185], v[186:189], v[18:33]
	s_waitcnt lgkmcnt(8)
	v_mfma_f32_32x32x16_bf16 v[34:49], v[178:181], v[190:193], v[34:49]
	v_mfma_f32_32x32x16_bf16 v[50:65], v[182:185], v[190:193], v[50:65]
	s_barrier
	ds_read_b128 v[162:165], v234 offset:18496
	ds_read_b128 v[170:173], v235 offset:18496
	s_waitcnt lgkmcnt(8)
	v_mfma_f32_32x32x16_bf16 v[2:17], v[130:133], v[138:141], v[2:17]
	ds_read_b128 v[166:169], v234 offset:23104
	ds_read_b128 v[174:177], v235 offset:23104
	s_waitcnt lgkmcnt(9)
	v_mfma_f32_32x32x16_bf16 v[18:33], v[134:137], v[138:141], v[18:33]
	ds_read_b128 v[178:181], v234 offset:18528
	ds_read_b128 v[186:189], v235 offset:18528
	s_waitcnt lgkmcnt(10)
	v_mfma_f32_32x32x16_bf16 v[34:49], v[130:133], v[142:145], v[34:49]
	ds_read_b128 v[182:185], v234 offset:23136
	ds_read_b128 v[190:193], v235 offset:23136
	v_mfma_f32_32x32x16_bf16 v[50:65], v[134:137], v[142:145], v[50:65]
	s_waitcnt lgkmcnt(10)
	v_mfma_f32_32x32x16_bf16 v[2:17], v[146:149], v[154:157], v[2:17]
	s_waitcnt lgkmcnt(9)
	v_mfma_f32_32x32x16_bf16 v[18:33], v[150:153], v[154:157], v[18:33]
	s_waitcnt lgkmcnt(8)
	v_mfma_f32_32x32x16_bf16 v[34:49], v[146:149], v[158:161], v[34:49]
	v_mfma_f32_32x32x16_bf16 v[50:65], v[150:153], v[158:161], v[50:65]
	ds_read_b128 v[130:133], v234 offset:36864
	ds_read_b128 v[138:141], v235 offset:36864
	s_waitcnt lgkmcnt(8)
	v_mfma_f32_32x32x16_bf16 v[2:17], v[162:165], v[170:173], v[2:17]
	ds_read_b128 v[134:137], v234 offset:41472
	ds_read_b128 v[142:145], v235 offset:41472
	s_waitcnt lgkmcnt(9)
	v_mfma_f32_32x32x16_bf16 v[18:33], v[166:169], v[170:173], v[18:33]
	ds_read_b128 v[146:149], v234 offset:36896
	ds_read_b128 v[154:157], v235 offset:36896
	s_waitcnt lgkmcnt(10)
	v_mfma_f32_32x32x16_bf16 v[34:49], v[162:165], v[174:177], v[34:49]
	ds_read_b128 v[150:153], v234 offset:41504
	ds_read_b128 v[158:161], v235 offset:41504
	v_mfma_f32_32x32x16_bf16 v[50:65], v[166:169], v[174:177], v[50:65]
	s_waitcnt lgkmcnt(10)
	v_mfma_f32_32x32x16_bf16 v[2:17], v[178:181], v[186:189], v[2:17]
	s_waitcnt lgkmcnt(9)
	v_mfma_f32_32x32x16_bf16 v[18:33], v[182:185], v[186:189], v[18:33]
	s_waitcnt lgkmcnt(8)
	v_mfma_f32_32x32x16_bf16 v[34:49], v[178:181], v[190:193], v[34:49]
	v_mfma_f32_32x32x16_bf16 v[50:65], v[182:185], v[190:193], v[50:65]
	s_barrier
; DI f32x16 mfma(bf16x8 a, bf16x8 b, f32x16 c) { return __builtin_amdgcn_mfma_f32_32x32x16_bf16(a, b, c, 0, 0, 0); }
; template <bool RFA, bool RFB, class LA, class LB, class EPI>
; DI void gemm_tile2s(u16* smem, int nk, LA la, LB lb, EPI epi) {
;     ...
;   auto compute = [&](int buf) __attribute__((always_inline)) {
;     const u16* Ab = As + buf * TILE_ELEMS + (wm * 64 + lr) * LDT + lh * 8;
;     const u16* Bb = Bs + buf * TILE_ELEMS + (wn * 32 + lr) * LDT + lh * 8;
; #pragma unroll
;     for (int ks = 0; ks < 4; ++ks) {
;       const bf16x8 a0 = *(const bf16x8*)(Ab + ks * 16);
;       const bf16x8 a1 = *(const bf16x8*)(Ab + 32 * LDT + ks * 16);
;       const bf16x8 b = *(const bf16x8*)(Bb + ks * 16);
;       acc[0] = mfma(a0, b, acc[0]);
;       acc[1] = mfma(a1, b, acc[1]);
;     }
;   };
;     ...
;     if (kt + 1 < nk) { stl(ra1, rb1, 1); if (kt + 3 < nk) ld(ra1, rb1, kt + 3); }
;     __syncthreads();
;     if (kt + 1 < nk) {
;       compute(1);
;       if (kt + 2 < nk) { stl(ra0, rb0, 0); if (kt + 4 < nk) ld(ra0, rb0, kt + 4); }
;       __syncthreads();
	ds_read_b128 v[162:165], v234 offset:36928
	ds_read_b128 v[170:173], v235 offset:36928
	s_waitcnt lgkmcnt(8)
	v_mfma_f32_32x32x16_bf16 v[2:17], v[130:133], v[138:141], v[2:17]
	ds_read_b128 v[166:169], v234 offset:41536
	ds_read_b128 v[174:177], v235 offset:41536
	s_waitcnt lgkmcnt(9)
	v_mfma_f32_32x32x16_bf16 v[18:33], v[134:137], v[138:141], v[18:33]
	ds_read_b128 v[178:181], v234 offset:36960
	ds_read_b128 v[186:189], v235 offset:36960
	s_waitcnt lgkmcnt(10)
	v_mfma_f32_32x32x16_bf16 v[34:49], v[130:133], v[142:145], v[34:49]
	ds_read_b128 v[182:185], v234 offset:41568
	ds_read_b128 v[190:193], v235 offset:41568
	v_mfma_f32_32x32x16_bf16 v[50:65], v[134:137], v[142:145], v[50:65]
	s_waitcnt lgkmcnt(10)
	v_mfma_f32_32x32x16_bf16 v[2:17], v[146:149], v[154:157], v[2:17]
	s_waitcnt lgkmcnt(9)
	v_mfma_f32_32x32x16_bf16 v[18:33], v[150:153], v[154:157], v[18:33]
	s_waitcnt lgkmcnt(8)
	v_mfma_f32_32x32x16_bf16 v[34:49], v[146:149], v[158:161], v[34:49]
	v_mfma_f32_32x32x16_bf16 v[50:65], v[150:153], v[158:161], v[50:65]
	ds_read_b128 v[130:133], v234
	ds_read_b128 v[138:141], v235
	s_waitcnt lgkmcnt(8)
	v_mfma_f32_32x32x16_bf16 v[2:17], v[162:165], v[170:173], v[2:17]
	ds_read_b128 v[134:137], v234 offset:4608
	ds_read_b128 v[142:145], v235 offset:4608
	s_waitcnt lgkmcnt(9)
	v_mfma_f32_32x32x16_bf16 v[18:33], v[166:169], v[170:173], v[18:33]
	ds_read_b128 v[146:149], v234 offset:32
	ds_read_b128 v[154:157], v235 offset:32
	s_waitcnt lgkmcnt(10)
	v_mfma_f32_32x32x16_bf16 v[34:49], v[162:165], v[174:177], v[34:49]
	ds_read_b128 v[150:153], v234 offset:4640
	ds_read_b128 v[158:161], v235 offset:4640
	v_mfma_f32_32x32x16_bf16 v[50:65], v[166:169], v[174:177], v[50:65]
	s_waitcnt lgkmcnt(10)
	v_mfma_f32_32x32x16_bf16 v[2:17], v[178:181], v[186:189], v[2:17]
	s_waitcnt lgkmcnt(9)
	v_mfma_f32_32x32x16_bf16 v[18:33], v[182:185], v[186:189], v[18:33]
	s_waitcnt lgkmcnt(8)
	v_mfma_f32_32x32x16_bf16 v[34:49], v[178:181], v[190:193], v[34:49]
	v_mfma_f32_32x32x16_bf16 v[50:65], v[182:185], v[190:193], v[50:65]
	s_barrier
	ds_read_b128 v[162:165], v234 offset:64
	ds_read_b128 v[170:173], v235 offset:64
	s_waitcnt lgkmcnt(8)
	v_mfma_f32_32x32x16_bf16 v[2:17], v[130:133], v[138:141], v[2:17]
	ds_read_b128 v[166:169], v234 offset:4672
	ds_read_b128 v[174:177], v235 offset:4672
	s_waitcnt lgkmcnt(9)
	v_mfma_f32_32x32x16_bf16 v[18:33], v[134:137], v[138:141], v[18:33]
	ds_read_b128 v[178:181], v234 offset:96
	ds_read_b128 v[186:189], v235 offset:96
	s_waitcnt lgkmcnt(10)
	v_mfma_f32_32x32x16_bf16 v[34:49], v[130:133], v[142:145], v[34:49]
	ds_read_b128 v[182:185], v234 offset:4704
	ds_read_b128 v[190:193], v235 offset:4704
	v_mfma_f32_32x32x16_bf16 v[50:65], v[134:137], v[142:145], v[50:65]
	s_waitcnt lgkmcnt(10)
	v_mfma_f32_32x32x16_bf16 v[2:17], v[146:149], v[154:157], v[2:17]
	s_waitcnt lgkmcnt(9)
	v_mfma_f32_32x32x16_bf16 v[18:33], v[150:153], v[154:157], v[18:33]
	s_waitcnt lgkmcnt(8)
	v_mfma_f32_32x32x16_bf16 v[34:49], v[146:149], v[158:161], v[34:49]
	v_mfma_f32_32x32x16_bf16 v[50:65], v[150:153], v[158:161], v[50:65]
	ds_read_b128 v[130:133], v234 offset:18432
	ds_read_b128 v[138:141], v235 offset:18432
	s_waitcnt lgkmcnt(8)
	v_mfma_f32_32x32x16_bf16 v[2:17], v[162:165], v[170:173], v[2:17]
	ds_read_b128 v[134:137], v234 offset:23040
	ds_read_b128 v[142:145], v235 offset:23040
	s_waitcnt lgkmcnt(9)
	v_mfma_f32_32x32x16_bf16 v[18:33], v[166:169], v[170:173], v[18:33]
	ds_read_b128 v[146:149], v234 offset:18464
	ds_read_b128 v[154:157], v235 offset:18464
	s_waitcnt lgkmcnt(10)
	v_mfma_f32_32x32x16_bf16 v[34:49], v[162:165], v[174:177], v[34:49]
	ds_read_b128 v[150:153], v234 offset:23072
	ds_read_b128 v[158:161], v235 offset:23072
	v_mfma_f32_32x32x16_bf16 v[50:65], v[166:169], v[174:177], v[50:65]
	s_waitcnt lgkmcnt(10)
	v_mfma_f32_32x32x16_bf16 v[2:17], v[178:181], v[186:189], v[2:17]
	s_waitcnt lgkmcnt(9)
	v_mfma_f32_32x32x16_bf16 v[18:33], v[182:185], v[186:189], v[18:33]
	s_waitcnt lgkmcnt(8)
	v_mfma_f32_32x32x16_bf16 v[34:49], v[178:181], v[190:193], v[34:49]
	v_mfma_f32_32x32x16_bf16 v[50:65], v[182:185], v[190:193], v[50:65]
	s_barrier
	ds_read_b128 v[162:165], v234 offset:18496
	ds_read_b128 v[170:173], v235 offset:18496
	s_waitcnt lgkmcnt(8)
	v_mfma_f32_32x32x16_bf16 v[2:17], v[130:133], v[138:141], v[2:17]
	ds_read_b128 v[166:169], v234 offset:23104
	ds_read_b128 v[174:177], v235 offset:23104
	s_waitcnt lgkmcnt(9)
	v_mfma_f32_32x32x16_bf16 v[18:33], v[134:137], v[138:141], v[18:33]
	ds_read_b128 v[178:181], v234 offset:18528
	ds_read_b128 v[186:189], v235 offset:18528
	s_waitcnt lgkmcnt(10)
	v_mfma_f32_32x32x16_bf16 v[34:49], v[130:133], v[142:145], v[34:49]
	ds_read_b128 v[182:185], v234 offset:23136
	ds_read_b128 v[190:193], v235 offset:23136
	v_mfma_f32_32x32x16_bf16 v[50:65], v[134:137], v[142:145], v[50:65]
	s_waitcnt lgkmcnt(10)
	v_mfma_f32_32x32x16_bf16 v[2:17], v[146:149], v[154:157], v[2:17]
	s_waitcnt lgkmcnt(9)
	v_mfma_f32_32x32x16_bf16 v[18:33], v[150:153], v[154:157], v[18:33]
	s_waitcnt lgkmcnt(8)
	v_mfma_f32_32x32x16_bf16 v[34:49], v[146:149], v[158:161], v[34:49]
	v_mfma_f32_32x32x16_bf16 v[50:65], v[150:153], v[158:161], v[50:65]
	ds_read_b128 v[130:133], v234 offset:36864
	ds_read_b128 v[138:141], v235 offset:36864
	s_waitcnt lgkmcnt(8)
	v_mfma_f32_32x32x16_bf16 v[2:17], v[162:165], v[170:173], v[2:17]
	ds_read_b128 v[134:137], v234 offset:41472
	ds_read_b128 v[142:145], v235 offset:41472
	s_waitcnt lgkmcnt(9)
	v_mfma_f32_32x32x16_bf16 v[18:33], v[166:169], v[170:173], v[18:33]
	ds_read_b128 v[146:149], v234 offset:36896
	ds_read_b128 v[154:157], v235 offset:36896
	s_waitcnt lgkmcnt(10)
	v_mfma_f32_32x32x16_bf16 v[34:49], v[162:165], v[174:177], v[34:49]
	ds_read_b128 v[150:153], v234 offset:41504
	ds_read_b128 v[158:161], v235 offset:41504
	v_mfma_f32_32x32x16_bf16 v[50:65], v[166:169], v[174:177], v[50:65]
	s_waitcnt lgkmcnt(10)
	v_mfma_f32_32x32x16_bf16 v[2:17], v[178:181], v[186:189], v[2:17]
	s_waitcnt lgkmcnt(9)
	v_mfma_f32_32x32x16_bf16 v[18:33], v[182:185], v[186:189], v[18:33]
	s_waitcnt lgkmcnt(8)
	v_mfma_f32_32x32x16_bf16 v[34:49], v[178:181], v[190:193], v[34:49]
	v_mfma_f32_32x32x16_bf16 v[50:65], v[182:185], v[190:193], v[50:65]
	s_barrier
; DI f32x16 mfma(bf16x8 a, bf16x8 b, f32x16 c) { return __builtin_amdgcn_mfma_f32_32x32x16_bf16(a, b, c, 0, 0, 0); }
; template <bool RFA, bool RFB, class LA, class LB, class EPI>
; DI void gemm_tile2s(u16* smem, int nk, LA la, LB lb, EPI epi) {
;     ...
;   auto compute = [&](int buf) __attribute__((always_inline)) {
;     const u16* Ab = As + buf * TILE_ELEMS + (wm * 64 + lr) * LDT + lh * 8;
;     const u16* Bb = Bs + buf * TILE_ELEMS + (wn * 32 + lr) * LDT + lh * 8;
; #pragma unroll
;     for (int ks = 0; ks < 4; ++ks) {
;       const bf16x8 a0 = *(const bf16x8*)(Ab + ks * 16);
;       const bf16x8 a1 = *(const bf16x8*)(Ab + 32 * LDT + ks * 16);
;       const bf16x8 b = *(const bf16x8*)(Bb + ks * 16);
;       acc[0] = mfma(a0, b, acc[0]);
;       acc[1] = mfma(a1, b, acc[1]);
;     }
;   };
;     ...
;     if (kt + 1 < nk) { stl(ra1, rb1, 1); if (kt + 3 < nk) ld(ra1, rb1, kt + 3); }
;     __syncthreads();
;     if (kt + 1 < nk) {
;       compute(1);
;       if (kt + 2 < nk) { stl(ra0, rb0, 0); if (kt + 4 < nk) ld(ra0, rb0, kt + 4); }
;       __syncthreads();
	ds_read_b128 v[162:165], v234 offset:36928
	ds_read_b128 v[170:173], v235 offset:36928
	s_waitcnt lgkmcnt(8)
	v_mfma_f32_32x32x16_bf16 v[2:17], v[130:133], v[138:141], v[2:17]
	ds_read_b128 v[166:169], v234 offset:41536
	ds_read_b128 v[174:177], v235 offset:41536
	s_waitcnt lgkmcnt(9)
	v_mfma_f32_32x32x16_bf16 v[18:33], v[134:137], v[138:141], v[18:33]
	ds_read_b128 v[178:181], v234 offset:36960
	ds_read_b128 v[186:189], v235 offset:36960
	s_waitcnt lgkmcnt(10)
	v_mfma_f32_32x32x16_bf16 v[34:49], v[130:133], v[142:145], v[34:49]
	ds_read_b128 v[182:185], v234 offset:41568
	ds_read_b128 v[190:193], v235 offset:41568
	v_mfma_f32_32x32x16_bf16 v[50:65], v[134:137], v[142:145], v[50:65]
	s_waitcnt lgkmcnt(10)
	v_mfma_f32_32x32x16_bf16 v[2:17], v[146:149], v[154:157], v[2:17]
	s_waitcnt lgkmcnt(9)
	v_mfma_f32_32x32x16_bf16 v[18:33], v[150:153], v[154:157], v[18:33]
	s_waitcnt lgkmcnt(8)
	v_mfma_f32_32x32x16_bf16 v[34:49], v[146:149], v[158:161], v[34:49]
	v_mfma_f32_32x32x16_bf16 v[50:65], v[150:153], v[158:161], v[50:65]
	ds_read_b128 v[130:133], v234
	ds_read_b128 v[138:141], v235
	s_waitcnt lgkmcnt(8)
	v_mfma_f32_32x32x16_bf16 v[2:17], v[162:165], v[170:173], v[2:17]
	ds_read_b128 v[134:137], v234 offset:4608
	ds_read_b128 v[142:145], v235 offset:4608
	s_waitcnt lgkmcnt(9)
	v_mfma_f32_32x32x16_bf16 v[18:33], v[166:169], v[170:173], v[18:33]
	ds_read_b128 v[146:149], v234 offset:32
	ds_read_b128 v[154:157], v235 offset:32
	s_waitcnt lgkmcnt(10)
	v_mfma_f32_32x32x16_bf16 v[34:49], v[162:165], v[174:177], v[34:49]
	ds_read_b128 v[150:153], v234 offset:4640
	ds_read_b128 v[158:161], v235 offset:4640
	v_mfma_f32_32x32x16_bf16 v[50:65], v[166:169], v[174:177], v[50:65]
	s_waitcnt lgkmcnt(10)
	v_mfma_f32_32x32x16_bf16 v[2:17], v[178:181], v[186:189], v[2:17]
	s_waitcnt lgkmcnt(9)
	v_mfma_f32_32x32x16_bf16 v[18:33], v[182:185], v[186:189], v[18:33]
	s_waitcnt lgkmcnt(8)
	v_mfma_f32_32x32x16_bf16 v[34:49], v[178:181], v[190:193], v[34:49]
	v_mfma_f32_32x32x16_bf16 v[50:65], v[182:185], v[190:193], v[50:65]
	s_barrier
	ds_read_b128 v[162:165], v234 offset:64
	ds_read_b128 v[170:173], v235 offset:64
	s_waitcnt lgkmcnt(8)
	v_mfma_f32_32x32x16_bf16 v[2:17], v[130:133], v[138:141], v[2:17]
	ds_read_b128 v[166:169], v234 offset:4672
	ds_read_b128 v[174:177], v235 offset:4672
	s_waitcnt lgkmcnt(9)
	v_mfma_f32_32x32x16_bf16 v[18:33], v[134:137], v[138:141], v[18:33]
	ds_read_b128 v[178:181], v234 offset:96
	ds_read_b128 v[186:189], v235 offset:96
	s_waitcnt lgkmcnt(10)
	v_mfma_f32_32x32x16_bf16 v[34:49], v[130:133], v[142:145], v[34:49]
	ds_read_b128 v[182:185], v234 offset:4704
	ds_read_b128 v[190:193], v235 offset:4704
	v_mfma_f32_32x32x16_bf16 v[50:65], v[134:137], v[142:145], v[50:65]
	s_waitcnt lgkmcnt(10)
	v_mfma_f32_32x32x16_bf16 v[2:17], v[146:149], v[154:157], v[2:17]
	s_waitcnt lgkmcnt(9)
	v_mfma_f32_32x32x16_bf16 v[18:33], v[150:153], v[154:157], v[18:33]
	s_waitcnt lgkmcnt(8)
	v_mfma_f32_32x32x16_bf16 v[34:49], v[146:149], v[158:161], v[34:49]
	v_mfma_f32_32x32x16_bf16 v[50:65], v[150:153], v[158:161], v[50:65]
	ds_read_b128 v[130:133], v234 offset:18432
	ds_read_b128 v[138:141], v235 offset:18432
	s_waitcnt lgkmcnt(8)
	v_mfma_f32_32x32x16_bf16 v[2:17], v[162:165], v[170:173], v[2:17]
	ds_read_b128 v[134:137], v234 offset:23040
	ds_read_b128 v[142:145], v235 offset:23040
	s_waitcnt lgkmcnt(9)
	v_mfma_f32_32x32x16_bf16 v[18:33], v[166:169], v[170:173], v[18:33]
	ds_read_b128 v[146:149], v234 offset:18464
	ds_read_b128 v[154:157], v235 offset:18464
	s_waitcnt lgkmcnt(10)
	v_mfma_f32_32x32x16_bf16 v[34:49], v[162:165], v[174:177], v[34:49]
	ds_read_b128 v[150:153], v234 offset:23072
	ds_read_b128 v[158:161], v235 offset:23072
	v_mfma_f32_32x32x16_bf16 v[50:65], v[166:169], v[174:177], v[50:65]
	s_waitcnt lgkmcnt(10)
	v_mfma_f32_32x32x16_bf16 v[2:17], v[178:181], v[186:189], v[2:17]
	s_waitcnt lgkmcnt(9)
	v_mfma_f32_32x32x16_bf16 v[18:33], v[182:185], v[186:189], v[18:33]
	s_waitcnt lgkmcnt(8)
	v_mfma_f32_32x32x16_bf16 v[34:49], v[178:181], v[190:193], v[34:49]
	v_mfma_f32_32x32x16_bf16 v[50:65], v[182:185], v[190:193], v[50:65]
	s_barrier
	ds_read_b128 v[162:165], v234 offset:18496
	ds_read_b128 v[170:173], v235 offset:18496
	s_waitcnt lgkmcnt(8)
	v_mfma_f32_32x32x16_bf16 v[2:17], v[130:133], v[138:141], v[2:17]
	ds_read_b128 v[166:169], v234 offset:23104
	ds_read_b128 v[174:177], v235 offset:23104
	s_waitcnt lgkmcnt(9)
	v_mfma_f32_32x32x16_bf16 v[18:33], v[134:137], v[138:141], v[18:33]
	ds_read_b128 v[178:181], v234 offset:18528
	ds_read_b128 v[186:189], v235 offset:18528
	s_waitcnt lgkmcnt(10)
	v_mfma_f32_32x32x16_bf16 v[34:49], v[130:133], v[142:145], v[34:49]
	ds_read_b128 v[182:185], v234 offset:23136
	ds_read_b128 v[190:193], v235 offset:23136
	v_mfma_f32_32x32x16_bf16 v[50:65], v[134:137], v[142:145], v[50:65]
	s_waitcnt lgkmcnt(10)
	v_mfma_f32_32x32x16_bf16 v[2:17], v[146:149], v[154:157], v[2:17]
	s_waitcnt lgkmcnt(9)
	v_mfma_f32_32x32x16_bf16 v[18:33], v[150:153], v[154:157], v[18:33]
	s_waitcnt lgkmcnt(8)
	v_mfma_f32_32x32x16_bf16 v[34:49], v[146:149], v[158:161], v[34:49]
	v_mfma_f32_32x32x16_bf16 v[50:65], v[150:153], v[158:161], v[50:65]
	ds_read_b128 v[130:133], v234 offset:36864
	ds_read_b128 v[138:141], v235 offset:36864
	s_waitcnt lgkmcnt(8)
	v_mfma_f32_32x32x16_bf16 v[2:17], v[162:165], v[170:173], v[2:17]
	ds_read_b128 v[134:137], v234 offset:41472
	ds_read_b128 v[142:145], v235 offset:41472
	s_waitcnt lgkmcnt(9)
	v_mfma_f32_32x32x16_bf16 v[18:33], v[166:169], v[170:173], v[18:33]
	ds_read_b128 v[146:149], v234 offset:36896
	ds_read_b128 v[154:157], v235 offset:36896
	s_waitcnt lgkmcnt(10)
	v_mfma_f32_32x32x16_bf16 v[34:49], v[162:165], v[174:177], v[34:49]
	ds_read_b128 v[150:153], v234 offset:41504
	ds_read_b128 v[158:161], v235 offset:41504
	v_mfma_f32_32x32x16_bf16 v[50:65], v[166:169], v[174:177], v[50:65]
	s_waitcnt lgkmcnt(10)
	v_mfma_f32_32x32x16_bf16 v[2:17], v[178:181], v[186:189], v[2:17]
	s_waitcnt lgkmcnt(9)
	v_mfma_f32_32x32x16_bf16 v[18:33], v[182:185], v[186:189], v[18:33]
	s_waitcnt lgkmcnt(8)
	v_mfma_f32_32x32x16_bf16 v[34:49], v[178:181], v[190:193], v[34:49]
	v_mfma_f32_32x32x16_bf16 v[50:65], v[182:185], v[190:193], v[50:65]
	s_barrier
; DI f32x16 mfma(bf16x8 a, bf16x8 b, f32x16 c) { return __builtin_amdgcn_mfma_f32_32x32x16_bf16(a, b, c, 0, 0, 0); }
; template <bool RFA, bool RFB, class LA, class LB, class EPI>
; DI void gemm_tile2s(u16* smem, int nk, LA la, LB lb, EPI epi) {
;     ...
;   auto compute = [&](int buf) __attribute__((always_inline)) {
;     const u16* Ab = As + buf * TILE_ELEMS + (wm * 64 + lr) * LDT + lh * 8;
;     const u16* Bb = Bs + buf * TILE_ELEMS + (wn * 32 + lr) * LDT + lh * 8;
; #pragma unroll
;     for (int ks = 0; ks < 4; ++ks) {
;       const bf16x8 a0 = *(const bf16x8*)(Ab + ks * 16);
;       const bf16x8 a1 = *(const bf16x8*)(Ab + 32 * LDT + ks * 16);
;       const bf16x8 b = *(const bf16x8*)(Bb + ks * 16);
;       acc[0] = mfma(a0, b, acc[0]);
;       acc[1] = mfma(a1, b, acc[1]);
;     }
;   };
;     ...
;     if (kt + 1 < nk) { stl(ra1, rb1, 1); if (kt + 3 < nk) ld(ra1, rb1, kt + 3); }
;     __syncthreads();
;     if (kt + 1 < nk) {
;       compute(1);
;       if (kt + 2 < nk) { stl(ra0, rb0, 0); if (kt + 4 < nk) ld(ra0, rb0, kt + 4); }
;       __syncthreads();
	ds_read_b128 v[162:165], v234 offset:36928
	ds_read_b128 v[170:173], v235 offset:36928
	s_waitcnt lgkmcnt(8)
	v_mfma_f32_32x32x16_bf16 v[2:17], v[130:133], v[138:141], v[2:17]
	ds_read_b128 v[166:169], v234 offset:41536
	ds_read_b128 v[174:177], v235 offset:41536
	s_waitcnt lgkmcnt(9)
	v_mfma_f32_32x32x16_bf16 v[18:33], v[134:137], v[138:141], v[18:33]
	ds_read_b128 v[178:181], v234 offset:36960
	ds_read_b128 v[186:189], v235 offset:36960
	s_waitcnt lgkmcnt(10)
	v_mfma_f32_32x32x16_bf16 v[34:49], v[130:133], v[142:145], v[34:49]
	ds_read_b128 v[182:185], v234 offset:41568
	ds_read_b128 v[190:193], v235 offset:41568
	v_mfma_f32_32x32x16_bf16 v[50:65], v[134:137], v[142:145], v[50:65]
	s_waitcnt lgkmcnt(10)
	v_mfma_f32_32x32x16_bf16 v[2:17], v[146:149], v[154:157], v[2:17]
	s_waitcnt lgkmcnt(9)
	v_mfma_f32_32x32x16_bf16 v[18:33], v[150:153], v[154:157], v[18:33]
	s_waitcnt lgkmcnt(8)
	v_mfma_f32_32x32x16_bf16 v[34:49], v[146:149], v[158:161], v[34:49]
	v_mfma_f32_32x32x16_bf16 v[50:65], v[150:153], v[158:161], v[50:65]
	ds_read_b128 v[130:133], v234
	ds_read_b128 v[138:141], v235
	s_waitcnt lgkmcnt(8)
	v_mfma_f32_32x32x16_bf16 v[2:17], v[162:165], v[170:173], v[2:17]
	ds_read_b128 v[134:137], v234 offset:4608
	ds_read_b128 v[142:145], v235 offset:4608
	s_waitcnt lgkmcnt(9)
	v_mfma_f32_32x32x16_bf16 v[18:33], v[166:169], v[170:173], v[18:33]
	ds_read_b128 v[146:149], v234 offset:32
	ds_read_b128 v[154:157], v235 offset:32
	s_waitcnt lgkmcnt(10)
	v_mfma_f32_32x32x16_bf16 v[34:49], v[162:165], v[174:177], v[34:49]
	ds_read_b128 v[150:153], v234 offset:4640
	ds_read_b128 v[158:161], v235 offset:4640
	v_mfma_f32_32x32x16_bf16 v[50:65], v[166:169], v[174:177], v[50:65]
	s_waitcnt lgkmcnt(10)
	v_mfma_f32_32x32x16_bf16 v[2:17], v[178:181], v[186:189], v[2:17]
	s_waitcnt lgkmcnt(9)
	v_mfma_f32_32x32x16_bf16 v[18:33], v[182:185], v[186:189], v[18:33]
	s_waitcnt lgkmcnt(8)
	v_mfma_f32_32x32x16_bf16 v[34:49], v[178:181], v[190:193], v[34:49]
	v_mfma_f32_32x32x16_bf16 v[50:65], v[182:185], v[190:193], v[50:65]
	s_barrier
	ds_read_b128 v[162:165], v234 offset:64
	ds_read_b128 v[170:173], v235 offset:64
	s_waitcnt lgkmcnt(8)
	v_mfma_f32_32x32x16_bf16 v[2:17], v[130:133], v[138:141], v[2:17]
	ds_read_b128 v[166:169], v234 offset:4672
	ds_read_b128 v[174:177], v235 offset:4672
	s_waitcnt lgkmcnt(9)
	v_mfma_f32_32x32x16_bf16 v[18:33], v[134:137], v[138:141], v[18:33]
	ds_read_b128 v[178:181], v234 offset:96
	ds_read_b128 v[186:189], v235 offset:96
	s_waitcnt lgkmcnt(10)
	v_mfma_f32_32x32x16_bf16 v[34:49], v[130:133], v[142:145], v[34:49]
	ds_read_b128 v[182:185], v234 offset:4704
	ds_read_b128 v[190:193], v235 offset:4704
	v_mfma_f32_32x32x16_bf16 v[50:65], v[134:137], v[142:145], v[50:65]
	s_waitcnt lgkmcnt(10)
	v_mfma_f32_32x32x16_bf16 v[2:17], v[146:149], v[154:157], v[2:17]
	s_waitcnt lgkmcnt(9)
	v_mfma_f32_32x32x16_bf16 v[18:33], v[150:153], v[154:157], v[18:33]
	s_waitcnt lgkmcnt(8)
	v_mfma_f32_32x32x16_bf16 v[34:49], v[146:149], v[158:161], v[34:49]
	v_mfma_f32_32x32x16_bf16 v[50:65], v[150:153], v[158:161], v[50:65]
	ds_read_b128 v[130:133], v234 offset:18432
	ds_read_b128 v[138:141], v235 offset:18432
	s_waitcnt lgkmcnt(8)
	v_mfma_f32_32x32x16_bf16 v[2:17], v[162:165], v[170:173], v[2:17]
	ds_read_b128 v[134:137], v234 offset:23040
	ds_read_b128 v[142:145], v235 offset:23040
	s_waitcnt lgkmcnt(9)
	v_mfma_f32_32x32x16_bf16 v[18:33], v[166:169], v[170:173], v[18:33]
	ds_read_b128 v[146:149], v234 offset:18464
	ds_read_b128 v[154:157], v235 offset:18464
	s_waitcnt lgkmcnt(10)
	v_mfma_f32_32x32x16_bf16 v[34:49], v[162:165], v[174:177], v[34:49]
	ds_read_b128 v[150:153], v234 offset:23072
	ds_read_b128 v[158:161], v235 offset:23072
	v_mfma_f32_32x32x16_bf16 v[50:65], v[166:169], v[174:177], v[50:65]
	s_waitcnt lgkmcnt(10)
	v_mfma_f32_32x32x16_bf16 v[2:17], v[178:181], v[186:189], v[2:17]
	s_waitcnt lgkmcnt(9)
	v_mfma_f32_32x32x16_bf16 v[18:33], v[182:185], v[186:189], v[18:33]
	s_waitcnt lgkmcnt(8)
	v_mfma_f32_32x32x16_bf16 v[34:49], v[178:181], v[190:193], v[34:49]
	v_mfma_f32_32x32x16_bf16 v[50:65], v[182:185], v[190:193], v[50:65]
	s_barrier
	ds_read_b128 v[162:165], v234 offset:18496
	ds_read_b128 v[170:173], v235 offset:18496
	s_waitcnt lgkmcnt(8)
	v_mfma_f32_32x32x16_bf16 v[2:17], v[130:133], v[138:141], v[2:17]
	ds_read_b128 v[166:169], v234 offset:23104
	ds_read_b128 v[174:177], v235 offset:23104
	s_waitcnt lgkmcnt(9)
	v_mfma_f32_32x32x16_bf16 v[18:33], v[134:137], v[138:141], v[18:33]
	ds_read_b128 v[178:181], v234 offset:18528
	ds_read_b128 v[186:189], v235 offset:18528
	s_waitcnt lgkmcnt(10)
	v_mfma_f32_32x32x16_bf16 v[34:49], v[130:133], v[142:145], v[34:49]
	ds_read_b128 v[182:185], v234 offset:23136
	ds_read_b128 v[190:193], v235 offset:23136
	v_mfma_f32_32x32x16_bf16 v[50:65], v[134:137], v[142:145], v[50:65]
	s_waitcnt lgkmcnt(10)
	v_mfma_f32_32x32x16_bf16 v[2:17], v[146:149], v[154:157], v[2:17]
	s_waitcnt lgkmcnt(9)
	v_mfma_f32_32x32x16_bf16 v[18:33], v[150:153], v[154:157], v[18:33]
	s_waitcnt lgkmcnt(8)
	v_mfma_f32_32x32x16_bf16 v[34:49], v[146:149], v[158:161], v[34:49]
	v_mfma_f32_32x32x16_bf16 v[50:65], v[150:153], v[158:161], v[50:65]
	ds_read_b128 v[130:133], v234 offset:36864
	ds_read_b128 v[138:141], v235 offset:36864
	s_waitcnt lgkmcnt(8)
	v_mfma_f32_32x32x16_bf16 v[2:17], v[162:165], v[170:173], v[2:17]
	ds_read_b128 v[134:137], v234 offset:41472
	ds_read_b128 v[142:145], v235 offset:41472
	s_waitcnt lgkmcnt(9)
	v_mfma_f32_32x32x16_bf16 v[18:33], v[166:169], v[170:173], v[18:33]
	ds_read_b128 v[146:149], v234 offset:36896
	ds_read_b128 v[154:157], v235 offset:36896
	s_waitcnt lgkmcnt(10)
	v_mfma_f32_32x32x16_bf16 v[34:49], v[162:165], v[174:177], v[34:49]
	ds_read_b128 v[150:153], v234 offset:41504
	ds_read_b128 v[158:161], v235 offset:41504
	v_mfma_f32_32x32x16_bf16 v[50:65], v[166:169], v[174:177], v[50:65]
	s_waitcnt lgkmcnt(10)
	v_mfma_f32_32x32x16_bf16 v[2:17], v[178:181], v[186:189], v[2:17]
	s_waitcnt lgkmcnt(9)
	v_mfma_f32_32x32x16_bf16 v[18:33], v[182:185], v[186:189], v[18:33]
	s_waitcnt lgkmcnt(8)
	v_mfma_f32_32x32x16_bf16 v[34:49], v[178:181], v[190:193], v[34:49]
	v_mfma_f32_32x32x16_bf16 v[50:65], v[182:185], v[190:193], v[50:65]
	s_barrier
; DI float bflo(unsigned w) { return __uint_as_float(w << 16); }
; DI float bfhi(unsigned w) { return __uint_as_float(w & 0xffff0000u); }
; template <class ACC>
; DI void merge_branch(const Prm& p, u16* smem, const u16* W, const u16* X, int ld, int bi, int n0, int m0, ACC& macc) {
;     ...
;   auto epi = [&](f32x16 (&acc)[2], int wm, int wn, int lane) __attribute__((always_inline)) {
;     const int lr = lane & 31, lh = lane >> 5;
;     const int tok = m0 + wn * 32 + lr;
; #pragma unroll
;     for (int i = 0; i < 2; ++i)
; #pragma unroll
;       for (int h2 = 0; h2 < 2; ++h2) {
;         const int n = n0 + wm * 64 + i * 32 + 16 * lh + 8 * h2;
;         const u32x4 gz = *(const u32x4*)(p.zg + (size_t)tok * 4096 + bi * 1024 + n);
; #pragma unroll
;         for (int e = 0; e < 4; ++e) {
;           macc[i][8 * h2 + 2 * e] += bflo(gz[e]) * acc[i][8 * h2 + 2 * e];
;           macc[i][8 * h2 + 2 * e + 1] += bfhi(gz[e]) * acc[i][8 * h2 + 2 * e + 1];
;         }
	ds_read_b128 v[162:165], v234 offset:36928
	ds_read_b128 v[170:173], v235 offset:36928
	s_waitcnt lgkmcnt(8)
	v_mfma_f32_32x32x16_bf16 v[2:17], v[130:133], v[138:141], v[2:17]
	ds_read_b128 v[166:169], v234 offset:41536
	ds_read_b128 v[174:177], v235 offset:41536
	s_waitcnt lgkmcnt(9)
	v_mfma_f32_32x32x16_bf16 v[18:33], v[134:137], v[138:141], v[18:33]
	ds_read_b128 v[178:181], v234 offset:36960
	ds_read_b128 v[186:189], v235 offset:36960
	s_waitcnt lgkmcnt(10)
	v_mfma_f32_32x32x16_bf16 v[34:49], v[130:133], v[142:145], v[34:49]
	ds_read_b128 v[182:185], v234 offset:41568
	ds_read_b128 v[190:193], v235 offset:41568
	v_mfma_f32_32x32x16_bf16 v[50:65], v[134:137], v[142:145], v[50:65]
	s_waitcnt lgkmcnt(10)
	v_mfma_f32_32x32x16_bf16 v[2:17], v[146:149], v[154:157], v[2:17]
	s_waitcnt lgkmcnt(9)
	v_mfma_f32_32x32x16_bf16 v[18:33], v[150:153], v[154:157], v[18:33]
	s_waitcnt lgkmcnt(8)
	v_mfma_f32_32x32x16_bf16 v[34:49], v[146:149], v[158:161], v[34:49]
	v_mfma_f32_32x32x16_bf16 v[50:65], v[150:153], v[158:161], v[50:65]
	ds_read_b128 v[130:133], v234
	ds_read_b128 v[138:141], v235
	s_waitcnt lgkmcnt(8)
	v_mfma_f32_32x32x16_bf16 v[2:17], v[162:165], v[170:173], v[2:17]
	ds_read_b128 v[134:137], v234 offset:4608
	ds_read_b128 v[142:145], v235 offset:4608
	s_waitcnt lgkmcnt(9)
	v_mfma_f32_32x32x16_bf16 v[18:33], v[166:169], v[170:173], v[18:33]
	ds_read_b128 v[146:149], v234 offset:32
	ds_read_b128 v[154:157], v235 offset:32
	s_waitcnt lgkmcnt(10)
	v_mfma_f32_32x32x16_bf16 v[34:49], v[162:165], v[174:177], v[34:49]
	ds_read_b128 v[150:153], v234 offset:4640
	ds_read_b128 v[158:161], v235 offset:4640
	v_mfma_f32_32x32x16_bf16 v[50:65], v[166:169], v[174:177], v[50:65]
	s_waitcnt lgkmcnt(10)
	v_mfma_f32_32x32x16_bf16 v[2:17], v[178:181], v[186:189], v[2:17]
	s_waitcnt lgkmcnt(9)
	v_mfma_f32_32x32x16_bf16 v[18:33], v[182:185], v[186:189], v[18:33]
	s_waitcnt lgkmcnt(8)
	v_mfma_f32_32x32x16_bf16 v[34:49], v[178:181], v[190:193], v[34:49]
	v_mfma_f32_32x32x16_bf16 v[50:65], v[182:185], v[190:193], v[50:65]
	s_waitcnt vmcnt(0)
	s_nop 15
	v_lshlrev_b32_e32 v244, 16, v194
	v_and_b32_e32 v245, 0xffff0000, v194
	v_pk_mul_f32 v[66:67], v[244:245], v[2:3]
	v_lshlrev_b32_e32 v246, 16, v195
	v_and_b32_e32 v247, 0xffff0000, v195
	v_pk_mul_f32 v[68:69], v[246:247], v[4:5]
	v_lshlrev_b32_e32 v248, 16, v196
	v_and_b32_e32 v249, 0xffff0000, v196
	v_pk_mul_f32 v[70:71], v[248:249], v[6:7]
	v_lshlrev_b32_e32 v250, 16, v197
	v_and_b32_e32 v251, 0xffff0000, v197
	v_pk_mul_f32 v[72:73], v[250:251], v[8:9]
	v_lshlrev_b32_e32 v244, 16, v198
	v_and_b32_e32 v245, 0xffff0000, v198
	v_pk_mul_f32 v[74:75], v[244:245], v[10:11]
	v_lshlrev_b32_e32 v246, 16, v199
	v_and_b32_e32 v247, 0xffff0000, v199
	v_pk_mul_f32 v[76:77], v[246:247], v[12:13]
	v_lshlrev_b32_e32 v248, 16, v200
	v_and_b32_e32 v249, 0xffff0000, v200
	v_pk_mul_f32 v[78:79], v[248:249], v[14:15]
	v_lshlrev_b32_e32 v250, 16, v201
	v_and_b32_e32 v251, 0xffff0000, v201
	v_pk_mul_f32 v[80:81], v[250:251], v[16:17]
	v_lshlrev_b32_e32 v244, 16, v202
	v_and_b32_e32 v245, 0xffff0000, v202
	v_pk_mul_f32 v[82:83], v[244:245], v[18:19]
	v_lshlrev_b32_e32 v246, 16, v203
	v_and_b32_e32 v247, 0xffff0000, v203
	v_pk_mul_f32 v[84:85], v[246:247], v[20:21]
	v_lshlrev_b32_e32 v248, 16, v204
	v_and_b32_e32 v249, 0xffff0000, v204
	v_pk_mul_f32 v[86:87], v[248:249], v[22:23]
	v_lshlrev_b32_e32 v250, 16, v205
	v_and_b32_e32 v251, 0xffff0000, v205
	v_pk_mul_f32 v[88:89], v[250:251], v[24:25]
	v_lshlrev_b32_e32 v244, 16, v206
	v_and_b32_e32 v245, 0xffff0000, v206
	v_pk_mul_f32 v[90:91], v[244:245], v[26:27]
	v_lshlrev_b32_e32 v246, 16, v207
	v_and_b32_e32 v247, 0xffff0000, v207
	v_pk_mul_f32 v[92:93], v[246:247], v[28:29]
	v_lshlrev_b32_e32 v248, 16, v208
	v_and_b32_e32 v249, 0xffff0000, v208
	v_pk_mul_f32 v[94:95], v[248:249], v[30:31]
	v_lshlrev_b32_e32 v250, 16, v209
	v_and_b32_e32 v251, 0xffff0000, v209
	v_pk_mul_f32 v[96:97], v[250:251], v[32:33]
	v_lshlrev_b32_e32 v244, 16, v210
	v_and_b32_e32 v245, 0xffff0000, v210
	v_pk_mul_f32 v[98:99], v[244:245], v[34:35]
	v_lshlrev_b32_e32 v246, 16, v211
	v_and_b32_e32 v247, 0xffff0000, v211
	v_pk_mul_f32 v[100:101], v[246:247], v[36:37]
	v_lshlrev_b32_e32 v248, 16, v212
	v_and_b32_e32 v249, 0xffff0000, v212
	v_pk_mul_f32 v[102:103], v[248:249], v[38:39]
	v_lshlrev_b32_e32 v250, 16, v213
	v_and_b32_e32 v251, 0xffff0000, v213
	v_pk_mul_f32 v[104:105], v[250:251], v[40:41]
	v_lshlrev_b32_e32 v244, 16, v214
	v_and_b32_e32 v245, 0xffff0000, v214
	v_pk_mul_f32 v[106:107], v[244:245], v[42:43]
	v_lshlrev_b32_e32 v246, 16, v215
	v_and_b32_e32 v247, 0xffff0000, v215
	v_pk_mul_f32 v[108:109], v[246:247], v[44:45]
	v_lshlrev_b32_e32 v248, 16, v216
	v_and_b32_e32 v249, 0xffff0000, v216
	v_pk_mul_f32 v[110:111], v[248:249], v[46:47]
	v_lshlrev_b32_e32 v250, 16, v217
	v_and_b32_e32 v251, 0xffff0000, v217
	v_pk_mul_f32 v[112:113], v[250:251], v[48:49]
	v_lshlrev_b32_e32 v244, 16, v218
	v_and_b32_e32 v245, 0xffff0000, v218
	v_pk_mul_f32 v[114:115], v[244:245], v[50:51]
	v_lshlrev_b32_e32 v246, 16, v219
	v_and_b32_e32 v247, 0xffff0000, v219
	v_pk_mul_f32 v[116:117], v[246:247], v[52:53]
	v_lshlrev_b32_e32 v248, 16, v220
	v_and_b32_e32 v249, 0xffff0000, v220
	v_pk_mul_f32 v[118:119], v[248:249], v[54:55]
	v_lshlrev_b32_e32 v250, 16, v221
	v_and_b32_e32 v251, 0xffff0000, v221
	v_pk_mul_f32 v[120:121], v[250:251], v[56:57]
	v_lshlrev_b32_e32 v244, 16, v226
	v_and_b32_e32 v245, 0xffff0000, v226
	v_pk_mul_f32 v[122:123], v[244:245], v[58:59]
	v_lshlrev_b32_e32 v246, 16, v227
	v_and_b32_e32 v247, 0xffff0000, v227
	v_pk_mul_f32 v[124:125], v[246:247], v[60:61]
	v_lshlrev_b32_e32 v248, 16, v228
	v_and_b32_e32 v249, 0xffff0000, v228
	v_pk_mul_f32 v[126:127], v[248:249], v[62:63]
	v_lshlrev_b32_e32 v250, 16, v229
	v_and_b32_e32 v251, 0xffff0000, v229
	v_pk_mul_f32 v[128:129], v[250:251], v[64:65]
	v_add_u32_e32 v244, 0x40000, v236
	global_load_dwordx4 v[194:197], v236, s[8:9] offset:2048
	global_load_dwordx4 v[198:201], v236, s[8:9] offset:2064
	global_load_dwordx4 v[202:205], v236, s[8:9] offset:2112
	global_load_dwordx4 v[206:209], v236, s[8:9] offset:2128
	global_load_dwordx4 v[210:213], v244, s[8:9] offset:2048
	global_load_dwordx4 v[214:217], v244, s[8:9] offset:2064
	global_load_dwordx4 v[218:221], v244, s[8:9] offset:2112
	global_load_dwordx4 v[226:229], v244, s[8:9] offset:2128
	s_barrier
; DI float bflo(unsigned w) { return __uint_as_float(w << 16); }
; DI float bfhi(unsigned w) { return __uint_as_float(w & 0xffff0000u); }
; DI f32x16 mfma(bf16x8 a, bf16x8 b, f32x16 c) { return __builtin_amdgcn_mfma_f32_32x32x16_bf16(a, b, c, 0, 0, 0); }
; template <bool RFA, bool RFB, class LA, class LB, class EPI>
; DI void gemm_tile2s(u16* smem, int nk, LA la, LB lb, EPI epi) {
;     ...
;   auto compute = [&](int buf) __attribute__((always_inline)) {
;     const u16* Ab = As + buf * TILE_ELEMS + (wm * 64 + lr) * LDT + lh * 8;
;     const u16* Bb = Bs + buf * TILE_ELEMS + (wn * 32 + lr) * LDT + lh * 8;
; #pragma unroll
;     for (int ks = 0; ks < 4; ++ks) {
;       const bf16x8 a0 = *(const bf16x8*)(Ab + ks * 16);
;       const bf16x8 a1 = *(const bf16x8*)(Ab + 32 * LDT + ks * 16);
;       const bf16x8 b = *(const bf16x8*)(Bb + ks * 16);
;       acc[0] = mfma(a0, b, acc[0]);
;       acc[1] = mfma(a1, b, acc[1]);
;     }
;   };
; template <class ACC>
; DI void merge_branch(const Prm& p, u16* smem, const u16* W, const u16* X, int ld, int bi, int n0, int m0, ACC& macc) {
;     ...
;   auto epi = [&](f32x16 (&acc)[2], int wm, int wn, int lane) __attribute__((always_inline)) {
;     const int lr = lane & 31, lh = lane >> 5;
;     const int tok = m0 + wn * 32 + lr;
; #pragma unroll
;     for (int i = 0; i < 2; ++i)
; #pragma unroll
;       for (int h2 = 0; h2 < 2; ++h2) {
;         const int n = n0 + wm * 64 + i * 32 + 16 * lh + 8 * h2;
;         const u32x4 gz = *(const u32x4*)(p.zg + (size_t)tok * 4096 + bi * 1024 + n);
; #pragma unroll
;         for (int e = 0; e < 4; ++e) {
;           macc[i][8 * h2 + 2 * e] += bflo(gz[e]) * acc[i][8 * h2 + 2 * e];
;           macc[i][8 * h2 + 2 * e + 1] += bfhi(gz[e]) * acc[i][8 * h2 + 2 * e + 1];
;         }
	ds_read_b128 v[162:165], v234 offset:64
	ds_read_b128 v[170:173], v235 offset:64
	s_waitcnt lgkmcnt(8)
	v_mfma_f32_32x32x16_bf16 v[2:17], v[130:133], v[138:141], 0
	ds_read_b128 v[166:169], v234 offset:4672
	ds_read_b128 v[174:177], v235 offset:4672
	s_waitcnt lgkmcnt(9)
	v_mfma_f32_32x32x16_bf16 v[18:33], v[134:137], v[138:141], 0
	ds_read_b128 v[178:181], v234 offset:96
	ds_read_b128 v[186:189], v235 offset:96
	s_waitcnt lgkmcnt(10)
	v_mfma_f32_32x32x16_bf16 v[34:49], v[130:133], v[142:145], 0
	ds_read_b128 v[182:185], v234 offset:4704
	ds_read_b128 v[190:193], v235 offset:4704
	v_mfma_f32_32x32x16_bf16 v[50:65], v[134:137], v[142:145], 0
	s_waitcnt lgkmcnt(10)
	v_mfma_f32_32x32x16_bf16 v[2:17], v[146:149], v[154:157], v[2:17]
	s_waitcnt lgkmcnt(9)
	v_mfma_f32_32x32x16_bf16 v[18:33], v[150:153], v[154:157], v[18:33]
	s_waitcnt lgkmcnt(8)
	v_mfma_f32_32x32x16_bf16 v[34:49], v[146:149], v[158:161], v[34:49]
	v_mfma_f32_32x32x16_bf16 v[50:65], v[150:153], v[158:161], v[50:65]
	ds_read_b128 v[130:133], v234 offset:18432
	ds_read_b128 v[138:141], v235 offset:18432
	s_waitcnt lgkmcnt(8)
	v_mfma_f32_32x32x16_bf16 v[2:17], v[162:165], v[170:173], v[2:17]
	ds_read_b128 v[134:137], v234 offset:23040
	ds_read_b128 v[142:145], v235 offset:23040
	s_waitcnt lgkmcnt(9)
	v_mfma_f32_32x32x16_bf16 v[18:33], v[166:169], v[170:173], v[18:33]
	ds_read_b128 v[146:149], v234 offset:18464
	ds_read_b128 v[154:157], v235 offset:18464
	s_waitcnt lgkmcnt(10)
	v_mfma_f32_32x32x16_bf16 v[34:49], v[162:165], v[174:177], v[34:49]
	ds_read_b128 v[150:153], v234 offset:23072
	ds_read_b128 v[158:161], v235 offset:23072
	v_mfma_f32_32x32x16_bf16 v[50:65], v[166:169], v[174:177], v[50:65]
	s_waitcnt lgkmcnt(10)
	v_mfma_f32_32x32x16_bf16 v[2:17], v[178:181], v[186:189], v[2:17]
	s_waitcnt lgkmcnt(9)
	v_mfma_f32_32x32x16_bf16 v[18:33], v[182:185], v[186:189], v[18:33]
	s_waitcnt lgkmcnt(8)
	v_mfma_f32_32x32x16_bf16 v[34:49], v[178:181], v[190:193], v[34:49]
	v_mfma_f32_32x32x16_bf16 v[50:65], v[182:185], v[190:193], v[50:65]
	s_barrier
	ds_read_b128 v[162:165], v234 offset:18496
	ds_read_b128 v[170:173], v235 offset:18496
	s_waitcnt lgkmcnt(8)
	v_mfma_f32_32x32x16_bf16 v[2:17], v[130:133], v[138:141], v[2:17]
	ds_read_b128 v[166:169], v234 offset:23104
	ds_read_b128 v[174:177], v235 offset:23104
	s_waitcnt lgkmcnt(9)
	v_mfma_f32_32x32x16_bf16 v[18:33], v[134:137], v[138:141], v[18:33]
	ds_read_b128 v[178:181], v234 offset:18528
	ds_read_b128 v[186:189], v235 offset:18528
	s_waitcnt lgkmcnt(10)
	v_mfma_f32_32x32x16_bf16 v[34:49], v[130:133], v[142:145], v[34:49]
	ds_read_b128 v[182:185], v234 offset:23136
	ds_read_b128 v[190:193], v235 offset:23136
	v_mfma_f32_32x32x16_bf16 v[50:65], v[134:137], v[142:145], v[50:65]
	s_waitcnt lgkmcnt(10)
	v_mfma_f32_32x32x16_bf16 v[2:17], v[146:149], v[154:157], v[2:17]
	s_waitcnt lgkmcnt(9)
	v_mfma_f32_32x32x16_bf16 v[18:33], v[150:153], v[154:157], v[18:33]
	s_waitcnt lgkmcnt(8)
	v_mfma_f32_32x32x16_bf16 v[34:49], v[146:149], v[158:161], v[34:49]
	v_mfma_f32_32x32x16_bf16 v[50:65], v[150:153], v[158:161], v[50:65]
	ds_read_b128 v[130:133], v234 offset:36864
	ds_read_b128 v[138:141], v235 offset:36864
	s_waitcnt lgkmcnt(8)
	v_mfma_f32_32x32x16_bf16 v[2:17], v[162:165], v[170:173], v[2:17]
	ds_read_b128 v[134:137], v234 offset:41472
	ds_read_b128 v[142:145], v235 offset:41472
	s_waitcnt lgkmcnt(9)
	v_mfma_f32_32x32x16_bf16 v[18:33], v[166:169], v[170:173], v[18:33]
	ds_read_b128 v[146:149], v234 offset:36896
	ds_read_b128 v[154:157], v235 offset:36896
	s_waitcnt lgkmcnt(10)
	v_mfma_f32_32x32x16_bf16 v[34:49], v[162:165], v[174:177], v[34:49]
	ds_read_b128 v[150:153], v234 offset:41504
	ds_read_b128 v[158:161], v235 offset:41504
	v_mfma_f32_32x32x16_bf16 v[50:65], v[166:169], v[174:177], v[50:65]
	s_waitcnt lgkmcnt(10)
	v_mfma_f32_32x32x16_bf16 v[2:17], v[178:181], v[186:189], v[2:17]
	s_waitcnt lgkmcnt(9)
	v_mfma_f32_32x32x16_bf16 v[18:33], v[182:185], v[186:189], v[18:33]
	s_waitcnt lgkmcnt(8)
	v_mfma_f32_32x32x16_bf16 v[34:49], v[178:181], v[190:193], v[34:49]
	v_mfma_f32_32x32x16_bf16 v[50:65], v[182:185], v[190:193], v[50:65]
	s_waitcnt vmcnt(0)
	s_nop 15
	v_lshlrev_b32_e32 v244, 16, v194
	v_and_b32_e32 v245, 0xffff0000, v194
	v_pk_fma_f32 v[66:67], v[244:245], v[2:3], v[66:67]
	v_lshlrev_b32_e32 v246, 16, v195
	v_and_b32_e32 v247, 0xffff0000, v195
	v_pk_fma_f32 v[68:69], v[246:247], v[4:5], v[68:69]
	v_lshlrev_b32_e32 v248, 16, v196
	v_and_b32_e32 v249, 0xffff0000, v196
	v_pk_fma_f32 v[70:71], v[248:249], v[6:7], v[70:71]
	v_lshlrev_b32_e32 v250, 16, v197
	v_and_b32_e32 v251, 0xffff0000, v197
	v_pk_fma_f32 v[72:73], v[250:251], v[8:9], v[72:73]
	v_lshlrev_b32_e32 v244, 16, v198
	v_and_b32_e32 v245, 0xffff0000, v198
	v_pk_fma_f32 v[74:75], v[244:245], v[10:11], v[74:75]
	v_lshlrev_b32_e32 v246, 16, v199
	v_and_b32_e32 v247, 0xffff0000, v199
	v_pk_fma_f32 v[76:77], v[246:247], v[12:13], v[76:77]
	v_lshlrev_b32_e32 v248, 16, v200
	v_and_b32_e32 v249, 0xffff0000, v200
	v_pk_fma_f32 v[78:79], v[248:249], v[14:15], v[78:79]
	v_lshlrev_b32_e32 v250, 16, v201
	v_and_b32_e32 v251, 0xffff0000, v201
	v_pk_fma_f32 v[80:81], v[250:251], v[16:17], v[80:81]
	v_lshlrev_b32_e32 v244, 16, v202
	v_and_b32_e32 v245, 0xffff0000, v202
	v_pk_fma_f32 v[82:83], v[244:245], v[18:19], v[82:83]
	v_lshlrev_b32_e32 v246, 16, v203
	v_and_b32_e32 v247, 0xffff0000, v203
	v_pk_fma_f32 v[84:85], v[246:247], v[20:21], v[84:85]
	v_lshlrev_b32_e32 v248, 16, v204
	v_and_b32_e32 v249, 0xffff0000, v204
	v_pk_fma_f32 v[86:87], v[248:249], v[22:23], v[86:87]
	v_lshlrev_b32_e32 v250, 16, v205
	v_and_b32_e32 v251, 0xffff0000, v205
	v_pk_fma_f32 v[88:89], v[250:251], v[24:25], v[88:89]
; DI float bflo(unsigned w) { return __uint_as_float(w << 16); }
; DI float bfhi(unsigned w) { return __uint_as_float(w & 0xffff0000u); }
; DI f32x16 mfma(bf16x8 a, bf16x8 b, f32x16 c) { return __builtin_amdgcn_mfma_f32_32x32x16_bf16(a, b, c, 0, 0, 0); }
; template <bool RFA, bool RFB, class LA, class LB, class EPI>
; DI void gemm_tile2s(u16* smem, int nk, LA la, LB lb, EPI epi) {
;     ...
;   auto compute = [&](int buf) __attribute__((always_inline)) {
;     const u16* Ab = As + buf * TILE_ELEMS + (wm * 64 + lr) * LDT + lh * 8;
;     const u16* Bb = Bs + buf * TILE_ELEMS + (wn * 32 + lr) * LDT + lh * 8;
; #pragma unroll
;     for (int ks = 0; ks < 4; ++ks) {
;       const bf16x8 a0 = *(const bf16x8*)(Ab + ks * 16);
;       const bf16x8 a1 = *(const bf16x8*)(Ab + 32 * LDT + ks * 16);
;       const bf16x8 b = *(const bf16x8*)(Bb + ks * 16);
;       acc[0] = mfma(a0, b, acc[0]);
;       acc[1] = mfma(a1, b, acc[1]);
;     }
;   };
; template <class ACC>
; DI void merge_branch(const Prm& p, u16* smem, const u16* W, const u16* X, int ld, int bi, int n0, int m0, ACC& macc) {
;     ...
;   auto epi = [&](f32x16 (&acc)[2], int wm, int wn, int lane) __attribute__((always_inline)) {
;     const int lr = lane & 31, lh = lane >> 5;
;     const int tok = m0 + wn * 32 + lr;
; #pragma unroll
;     for (int i = 0; i < 2; ++i)
; #pragma unroll
;       for (int h2 = 0; h2 < 2; ++h2) {
;         const int n = n0 + wm * 64 + i * 32 + 16 * lh + 8 * h2;
;         const u32x4 gz = *(const u32x4*)(p.zg + (size_t)tok * 4096 + bi * 1024 + n);
; #pragma unroll
;         for (int e = 0; e < 4; ++e) {
;           macc[i][8 * h2 + 2 * e] += bflo(gz[e]) * acc[i][8 * h2 + 2 * e];
;           macc[i][8 * h2 + 2 * e + 1] += bfhi(gz[e]) * acc[i][8 * h2 + 2 * e + 1];
;         }
	v_lshlrev_b32_e32 v244, 16, v206
	v_and_b32_e32 v245, 0xffff0000, v206
	v_pk_fma_f32 v[90:91], v[244:245], v[26:27], v[90:91]
	v_lshlrev_b32_e32 v246, 16, v207
	v_and_b32_e32 v247, 0xffff0000, v207
	v_pk_fma_f32 v[92:93], v[246:247], v[28:29], v[92:93]
	v_lshlrev_b32_e32 v248, 16, v208
	v_and_b32_e32 v249, 0xffff0000, v208
	v_pk_fma_f32 v[94:95], v[248:249], v[30:31], v[94:95]
	v_lshlrev_b32_e32 v250, 16, v209
	v_and_b32_e32 v251, 0xffff0000, v209
	v_pk_fma_f32 v[96:97], v[250:251], v[32:33], v[96:97]
	v_lshlrev_b32_e32 v244, 16, v210
	v_and_b32_e32 v245, 0xffff0000, v210
	v_pk_fma_f32 v[98:99], v[244:245], v[34:35], v[98:99]
	v_lshlrev_b32_e32 v246, 16, v211
	v_and_b32_e32 v247, 0xffff0000, v211
	v_pk_fma_f32 v[100:101], v[246:247], v[36:37], v[100:101]
	v_lshlrev_b32_e32 v248, 16, v212
	v_and_b32_e32 v249, 0xffff0000, v212
	v_pk_fma_f32 v[102:103], v[248:249], v[38:39], v[102:103]
	v_lshlrev_b32_e32 v250, 16, v213
	v_and_b32_e32 v251, 0xffff0000, v213
	v_pk_fma_f32 v[104:105], v[250:251], v[40:41], v[104:105]
	v_lshlrev_b32_e32 v244, 16, v214
	v_and_b32_e32 v245, 0xffff0000, v214
	v_pk_fma_f32 v[106:107], v[244:245], v[42:43], v[106:107]
	v_lshlrev_b32_e32 v246, 16, v215
	v_and_b32_e32 v247, 0xffff0000, v215
	v_pk_fma_f32 v[108:109], v[246:247], v[44:45], v[108:109]
	v_lshlrev_b32_e32 v248, 16, v216
	v_and_b32_e32 v249, 0xffff0000, v216
	v_pk_fma_f32 v[110:111], v[248:249], v[46:47], v[110:111]
	v_lshlrev_b32_e32 v250, 16, v217
	v_and_b32_e32 v251, 0xffff0000, v217
	v_pk_fma_f32 v[112:113], v[250:251], v[48:49], v[112:113]
	v_lshlrev_b32_e32 v244, 16, v218
	v_and_b32_e32 v245, 0xffff0000, v218
	v_pk_fma_f32 v[114:115], v[244:245], v[50:51], v[114:115]
	v_lshlrev_b32_e32 v246, 16, v219
	v_and_b32_e32 v247, 0xffff0000, v219
	v_pk_fma_f32 v[116:117], v[246:247], v[52:53], v[116:117]
	v_lshlrev_b32_e32 v248, 16, v220
	v_and_b32_e32 v249, 0xffff0000, v220
	v_pk_fma_f32 v[118:119], v[248:249], v[54:55], v[118:119]
	v_lshlrev_b32_e32 v250, 16, v221
	v_and_b32_e32 v251, 0xffff0000, v221
	v_pk_fma_f32 v[120:121], v[250:251], v[56:57], v[120:121]
	v_lshlrev_b32_e32 v244, 16, v226
	v_and_b32_e32 v245, 0xffff0000, v226
	v_pk_fma_f32 v[122:123], v[244:245], v[58:59], v[122:123]
	v_lshlrev_b32_e32 v246, 16, v227
	v_and_b32_e32 v247, 0xffff0000, v227
	v_pk_fma_f32 v[124:125], v[246:247], v[60:61], v[124:125]
	v_lshlrev_b32_e32 v248, 16, v228
	v_and_b32_e32 v249, 0xffff0000, v228
	v_pk_fma_f32 v[126:127], v[248:249], v[62:63], v[126:127]
	v_lshlrev_b32_e32 v250, 16, v229
	v_and_b32_e32 v251, 0xffff0000, v229
	v_pk_fma_f32 v[128:129], v[250:251], v[64:65], v[128:129]
	v_add_u32_e32 v244, 0x40000, v236
	global_load_dwordx4 v[194:197], v236, s[10:11]
	global_load_dwordx4 v[198:201], v236, s[10:11] offset:16
	global_load_dwordx4 v[202:205], v236, s[10:11] offset:64
	global_load_dwordx4 v[206:209], v236, s[10:11] offset:80
	global_load_dwordx4 v[210:213], v244, s[10:11]
	global_load_dwordx4 v[214:217], v244, s[10:11] offset:16
	global_load_dwordx4 v[218:221], v244, s[10:11] offset:64
	global_load_dwordx4 v[226:229], v244, s[10:11] offset:80
	s_barrier
	ds_read_b128 v[162:165], v234 offset:36928
	ds_read_b128 v[170:173], v235 offset:36928
	s_waitcnt lgkmcnt(8)
	v_mfma_f32_32x32x16_bf16 v[2:17], v[130:133], v[138:141], 0
	ds_read_b128 v[166:169], v234 offset:41536
	ds_read_b128 v[174:177], v235 offset:41536
	s_waitcnt lgkmcnt(9)
	v_mfma_f32_32x32x16_bf16 v[18:33], v[134:137], v[138:141], 0
	ds_read_b128 v[178:181], v234 offset:36960
	ds_read_b128 v[186:189], v235 offset:36960
	s_waitcnt lgkmcnt(10)
	v_mfma_f32_32x32x16_bf16 v[34:49], v[130:133], v[142:145], 0
	ds_read_b128 v[182:185], v234 offset:41568
	ds_read_b128 v[190:193], v235 offset:41568
	v_mfma_f32_32x32x16_bf16 v[50:65], v[134:137], v[142:145], 0
	s_waitcnt lgkmcnt(10)
	v_mfma_f32_32x32x16_bf16 v[2:17], v[146:149], v[154:157], v[2:17]
	s_waitcnt lgkmcnt(9)
	v_mfma_f32_32x32x16_bf16 v[18:33], v[150:153], v[154:157], v[18:33]
	s_waitcnt lgkmcnt(8)
	v_mfma_f32_32x32x16_bf16 v[34:49], v[146:149], v[158:161], v[34:49]
	v_mfma_f32_32x32x16_bf16 v[50:65], v[150:153], v[158:161], v[50:65]
	ds_read_b128 v[130:133], v234
	ds_read_b128 v[138:141], v235
	s_waitcnt lgkmcnt(8)
	v_mfma_f32_32x32x16_bf16 v[2:17], v[162:165], v[170:173], v[2:17]
	ds_read_b128 v[134:137], v234 offset:4608
	ds_read_b128 v[142:145], v235 offset:4608
	s_waitcnt lgkmcnt(9)
	v_mfma_f32_32x32x16_bf16 v[18:33], v[166:169], v[170:173], v[18:33]
	ds_read_b128 v[146:149], v234 offset:32
	ds_read_b128 v[154:157], v235 offset:32
	s_waitcnt lgkmcnt(10)
	v_mfma_f32_32x32x16_bf16 v[34:49], v[162:165], v[174:177], v[34:49]
	ds_read_b128 v[150:153], v234 offset:4640
	ds_read_b128 v[158:161], v235 offset:4640
	v_mfma_f32_32x32x16_bf16 v[50:65], v[166:169], v[174:177], v[50:65]
	s_waitcnt lgkmcnt(10)
	v_mfma_f32_32x32x16_bf16 v[2:17], v[178:181], v[186:189], v[2:17]
	s_waitcnt lgkmcnt(9)
	v_mfma_f32_32x32x16_bf16 v[18:33], v[182:185], v[186:189], v[18:33]
	s_waitcnt lgkmcnt(8)
	v_mfma_f32_32x32x16_bf16 v[34:49], v[178:181], v[190:193], v[34:49]
	v_mfma_f32_32x32x16_bf16 v[50:65], v[182:185], v[190:193], v[50:65]
	s_barrier
; DI f32x16 mfma(bf16x8 a, bf16x8 b, f32x16 c) { return __builtin_amdgcn_mfma_f32_32x32x16_bf16(a, b, c, 0, 0, 0); }
; template <bool RFA, bool RFB, class LA, class LB, class EPI>
; DI void gemm_tile2s(u16* smem, int nk, LA la, LB lb, EPI epi) {
;     ...
;   auto compute = [&](int buf) __attribute__((always_inline)) {
;     const u16* Ab = As + buf * TILE_ELEMS + (wm * 64 + lr) * LDT + lh * 8;
;     const u16* Bb = Bs + buf * TILE_ELEMS + (wn * 32 + lr) * LDT + lh * 8;
; #pragma unroll
;     for (int ks = 0; ks < 4; ++ks) {
;       const bf16x8 a0 = *(const bf16x8*)(Ab + ks * 16);
;       const bf16x8 a1 = *(const bf16x8*)(Ab + 32 * LDT + ks * 16);
;       const bf16x8 b = *(const bf16x8*)(Bb + ks * 16);
;       acc[0] = mfma(a0, b, acc[0]);
;       acc[1] = mfma(a1, b, acc[1]);
;     }
;   };
	ds_read_b128 v[162:165], v234 offset:64
	ds_read_b128 v[170:173], v235 offset:64
	s_waitcnt lgkmcnt(8)
	v_mfma_f32_32x32x16_bf16 v[2:17], v[130:133], v[138:141], v[2:17]
	ds_read_b128 v[166:169], v234 offset:4672
	ds_read_b128 v[174:177], v235 offset:4672
	s_waitcnt lgkmcnt(9)
	v_mfma_f32_32x32x16_bf16 v[18:33], v[134:137], v[138:141], v[18:33]
	ds_read_b128 v[178:181], v234 offset:96
	ds_read_b128 v[186:189], v235 offset:96
	s_waitcnt lgkmcnt(10)
	v_mfma_f32_32x32x16_bf16 v[34:49], v[130:133], v[142:145], v[34:49]
	ds_read_b128 v[182:185], v234 offset:4704
	ds_read_b128 v[190:193], v235 offset:4704
	v_mfma_f32_32x32x16_bf16 v[50:65], v[134:137], v[142:145], v[50:65]
	s_waitcnt lgkmcnt(10)
	v_mfma_f32_32x32x16_bf16 v[2:17], v[146:149], v[154:157], v[2:17]
	s_waitcnt lgkmcnt(9)
	v_mfma_f32_32x32x16_bf16 v[18:33], v[150:153], v[154:157], v[18:33]
	s_waitcnt lgkmcnt(8)
	v_mfma_f32_32x32x16_bf16 v[34:49], v[146:149], v[158:161], v[34:49]
	v_mfma_f32_32x32x16_bf16 v[50:65], v[150:153], v[158:161], v[50:65]
	ds_read_b128 v[130:133], v234 offset:18432
	ds_read_b128 v[138:141], v235 offset:18432
	s_waitcnt lgkmcnt(8)
	v_mfma_f32_32x32x16_bf16 v[2:17], v[162:165], v[170:173], v[2:17]
	ds_read_b128 v[134:137], v234 offset:23040
	ds_read_b128 v[142:145], v235 offset:23040
	s_waitcnt lgkmcnt(9)
	v_mfma_f32_32x32x16_bf16 v[18:33], v[166:169], v[170:173], v[18:33]
	ds_read_b128 v[146:149], v234 offset:18464
	ds_read_b128 v[154:157], v235 offset:18464
	s_waitcnt lgkmcnt(10)
	v_mfma_f32_32x32x16_bf16 v[34:49], v[162:165], v[174:177], v[34:49]
	ds_read_b128 v[150:153], v234 offset:23072
	ds_read_b128 v[158:161], v235 offset:23072
	v_mfma_f32_32x32x16_bf16 v[50:65], v[166:169], v[174:177], v[50:65]
	s_waitcnt lgkmcnt(10)
	v_mfma_f32_32x32x16_bf16 v[2:17], v[178:181], v[186:189], v[2:17]
	s_waitcnt lgkmcnt(9)
	v_mfma_f32_32x32x16_bf16 v[18:33], v[182:185], v[186:189], v[18:33]
	s_waitcnt lgkmcnt(8)
	v_mfma_f32_32x32x16_bf16 v[34:49], v[178:181], v[190:193], v[34:49]
	v_mfma_f32_32x32x16_bf16 v[50:65], v[182:185], v[190:193], v[50:65]
	s_barrier
	ds_read_b128 v[162:165], v234 offset:18496
	ds_read_b128 v[170:173], v235 offset:18496
	s_waitcnt lgkmcnt(8)
	v_mfma_f32_32x32x16_bf16 v[2:17], v[130:133], v[138:141], v[2:17]
	ds_read_b128 v[166:169], v234 offset:23104
	ds_read_b128 v[174:177], v235 offset:23104
	s_waitcnt lgkmcnt(9)
	v_mfma_f32_32x32x16_bf16 v[18:33], v[134:137], v[138:141], v[18:33]
	ds_read_b128 v[178:181], v234 offset:18528
	ds_read_b128 v[186:189], v235 offset:18528
	s_waitcnt lgkmcnt(10)
	v_mfma_f32_32x32x16_bf16 v[34:49], v[130:133], v[142:145], v[34:49]
	ds_read_b128 v[182:185], v234 offset:23136
	ds_read_b128 v[190:193], v235 offset:23136
	v_mfma_f32_32x32x16_bf16 v[50:65], v[134:137], v[142:145], v[50:65]
	s_waitcnt lgkmcnt(10)
	v_mfma_f32_32x32x16_bf16 v[2:17], v[146:149], v[154:157], v[2:17]
	s_waitcnt lgkmcnt(9)
	v_mfma_f32_32x32x16_bf16 v[18:33], v[150:153], v[154:157], v[18:33]
	s_waitcnt lgkmcnt(8)
	v_mfma_f32_32x32x16_bf16 v[34:49], v[146:149], v[158:161], v[34:49]
	v_mfma_f32_32x32x16_bf16 v[50:65], v[150:153], v[158:161], v[50:65]
	ds_read_b128 v[130:133], v234 offset:36864
	ds_read_b128 v[138:141], v235 offset:36864
	s_waitcnt lgkmcnt(8)
	v_mfma_f32_32x32x16_bf16 v[2:17], v[162:165], v[170:173], v[2:17]
	ds_read_b128 v[134:137], v234 offset:41472
	ds_read_b128 v[142:145], v235 offset:41472
	s_waitcnt lgkmcnt(9)
	v_mfma_f32_32x32x16_bf16 v[18:33], v[166:169], v[170:173], v[18:33]
	ds_read_b128 v[146:149], v234 offset:36896
	ds_read_b128 v[154:157], v235 offset:36896
	s_waitcnt lgkmcnt(10)
	v_mfma_f32_32x32x16_bf16 v[34:49], v[162:165], v[174:177], v[34:49]
	ds_read_b128 v[150:153], v234 offset:41504
	ds_read_b128 v[158:161], v235 offset:41504
	v_mfma_f32_32x32x16_bf16 v[50:65], v[166:169], v[174:177], v[50:65]
	s_waitcnt lgkmcnt(10)
	v_mfma_f32_32x32x16_bf16 v[2:17], v[178:181], v[186:189], v[2:17]
	s_waitcnt lgkmcnt(9)
	v_mfma_f32_32x32x16_bf16 v[18:33], v[182:185], v[186:189], v[18:33]
	s_waitcnt lgkmcnt(8)
	v_mfma_f32_32x32x16_bf16 v[34:49], v[178:181], v[190:193], v[34:49]
	v_mfma_f32_32x32x16_bf16 v[50:65], v[182:185], v[190:193], v[50:65]
	s_barrier
	ds_read_b128 v[162:165], v234 offset:36928
	ds_read_b128 v[170:173], v235 offset:36928
	s_waitcnt lgkmcnt(8)
	v_mfma_f32_32x32x16_bf16 v[2:17], v[130:133], v[138:141], v[2:17]
	ds_read_b128 v[166:169], v234 offset:41536
	ds_read_b128 v[174:177], v235 offset:41536
	s_waitcnt lgkmcnt(9)
	v_mfma_f32_32x32x16_bf16 v[18:33], v[134:137], v[138:141], v[18:33]
	ds_read_b128 v[178:181], v234 offset:36960
	ds_read_b128 v[186:189], v235 offset:36960
	s_waitcnt lgkmcnt(10)
	v_mfma_f32_32x32x16_bf16 v[34:49], v[130:133], v[142:145], v[34:49]
	ds_read_b128 v[182:185], v234 offset:41568
	ds_read_b128 v[190:193], v235 offset:41568
	v_mfma_f32_32x32x16_bf16 v[50:65], v[134:137], v[142:145], v[50:65]
	s_waitcnt lgkmcnt(10)
	v_mfma_f32_32x32x16_bf16 v[2:17], v[146:149], v[154:157], v[2:17]
	s_waitcnt lgkmcnt(9)
	v_mfma_f32_32x32x16_bf16 v[18:33], v[150:153], v[154:157], v[18:33]
	s_waitcnt lgkmcnt(8)
	v_mfma_f32_32x32x16_bf16 v[34:49], v[146:149], v[158:161], v[34:49]
	v_mfma_f32_32x32x16_bf16 v[50:65], v[150:153], v[158:161], v[50:65]
	ds_read_b128 v[130:133], v234
	ds_read_b128 v[138:141], v235
	s_waitcnt lgkmcnt(8)
	v_mfma_f32_32x32x16_bf16 v[2:17], v[162:165], v[170:173], v[2:17]
	ds_read_b128 v[134:137], v234 offset:4608
	ds_read_b128 v[142:145], v235 offset:4608
	s_waitcnt lgkmcnt(9)
	v_mfma_f32_32x32x16_bf16 v[18:33], v[166:169], v[170:173], v[18:33]
	ds_read_b128 v[146:149], v234 offset:32
	ds_read_b128 v[154:157], v235 offset:32
	s_waitcnt lgkmcnt(10)
	v_mfma_f32_32x32x16_bf16 v[34:49], v[162:165], v[174:177], v[34:49]
	ds_read_b128 v[150:153], v234 offset:4640
	ds_read_b128 v[158:161], v235 offset:4640
	v_mfma_f32_32x32x16_bf16 v[50:65], v[166:169], v[174:177], v[50:65]
	s_waitcnt lgkmcnt(10)
	v_mfma_f32_32x32x16_bf16 v[2:17], v[178:181], v[186:189], v[2:17]
	s_waitcnt lgkmcnt(9)
	v_mfma_f32_32x32x16_bf16 v[18:33], v[182:185], v[186:189], v[18:33]
	s_waitcnt lgkmcnt(8)
	v_mfma_f32_32x32x16_bf16 v[34:49], v[178:181], v[190:193], v[34:49]
	v_mfma_f32_32x32x16_bf16 v[50:65], v[182:185], v[190:193], v[50:65]
	s_barrier
; DI float bflo(unsigned w) { return __uint_as_float(w << 16); }
; DI float bfhi(unsigned w) { return __uint_as_float(w & 0xffff0000u); }
; DI f32x16 mfma(bf16x8 a, bf16x8 b, f32x16 c) { return __builtin_amdgcn_mfma_f32_32x32x16_bf16(a, b, c, 0, 0, 0); }
; template <bool RFA, bool RFB, class LA, class LB, class EPI>
; DI void gemm_tile2s(u16* smem, int nk, LA la, LB lb, EPI epi) {
;     ...
;   auto compute = [&](int buf) __attribute__((always_inline)) {
;     const u16* Ab = As + buf * TILE_ELEMS + (wm * 64 + lr) * LDT + lh * 8;
;     const u16* Bb = Bs + buf * TILE_ELEMS + (wn * 32 + lr) * LDT + lh * 8;
; #pragma unroll
;     for (int ks = 0; ks < 4; ++ks) {
;       const bf16x8 a0 = *(const bf16x8*)(Ab + ks * 16);
;       const bf16x8 a1 = *(const bf16x8*)(Ab + 32 * LDT + ks * 16);
;       const bf16x8 b = *(const bf16x8*)(Bb + ks * 16);
;       acc[0] = mfma(a0, b, acc[0]);
;       acc[1] = mfma(a1, b, acc[1]);
;     }
;   };
; template <class ACC>
; DI void merge_branch(const Prm& p, u16* smem, const u16* W, const u16* X, int ld, int bi, int n0, int m0, ACC& macc) {
;     ...
;   auto epi = [&](f32x16 (&acc)[2], int wm, int wn, int lane) __attribute__((always_inline)) {
;     const int lr = lane & 31, lh = lane >> 5;
;     const int tok = m0 + wn * 32 + lr;
; #pragma unroll
;     for (int i = 0; i < 2; ++i)
; #pragma unroll
;       for (int h2 = 0; h2 < 2; ++h2) {
;         const int n = n0 + wm * 64 + i * 32 + 16 * lh + 8 * h2;
;         const u32x4 gz = *(const u32x4*)(p.zg + (size_t)tok * 4096 + bi * 1024 + n);
; #pragma unroll
;         for (int e = 0; e < 4; ++e) {
;           macc[i][8 * h2 + 2 * e] += bflo(gz[e]) * acc[i][8 * h2 + 2 * e];
;           macc[i][8 * h2 + 2 * e + 1] += bfhi(gz[e]) * acc[i][8 * h2 + 2 * e + 1];
;         }
	ds_read_b128 v[162:165], v234 offset:64
	ds_read_b128 v[170:173], v235 offset:64
	s_waitcnt lgkmcnt(8)
	v_mfma_f32_32x32x16_bf16 v[2:17], v[130:133], v[138:141], v[2:17]
	ds_read_b128 v[166:169], v234 offset:4672
	ds_read_b128 v[174:177], v235 offset:4672
	s_waitcnt lgkmcnt(9)
	v_mfma_f32_32x32x16_bf16 v[18:33], v[134:137], v[138:141], v[18:33]
	ds_read_b128 v[178:181], v234 offset:96
	ds_read_b128 v[186:189], v235 offset:96
	s_waitcnt lgkmcnt(10)
	v_mfma_f32_32x32x16_bf16 v[34:49], v[130:133], v[142:145], v[34:49]
	ds_read_b128 v[182:185], v234 offset:4704
	ds_read_b128 v[190:193], v235 offset:4704
	v_mfma_f32_32x32x16_bf16 v[50:65], v[134:137], v[142:145], v[50:65]
	s_waitcnt lgkmcnt(10)
	v_mfma_f32_32x32x16_bf16 v[2:17], v[146:149], v[154:157], v[2:17]
	s_waitcnt lgkmcnt(9)
	v_mfma_f32_32x32x16_bf16 v[18:33], v[150:153], v[154:157], v[18:33]
	s_waitcnt lgkmcnt(8)
	v_mfma_f32_32x32x16_bf16 v[34:49], v[146:149], v[158:161], v[34:49]
	v_mfma_f32_32x32x16_bf16 v[50:65], v[150:153], v[158:161], v[50:65]
	ds_read_b128 v[130:133], v234 offset:18432
	ds_read_b128 v[138:141], v235 offset:18432
	s_waitcnt lgkmcnt(8)
	v_mfma_f32_32x32x16_bf16 v[2:17], v[162:165], v[170:173], v[2:17]
	ds_read_b128 v[134:137], v234 offset:23040
	ds_read_b128 v[142:145], v235 offset:23040
	s_waitcnt lgkmcnt(9)
	v_mfma_f32_32x32x16_bf16 v[18:33], v[166:169], v[170:173], v[18:33]
	ds_read_b128 v[146:149], v234 offset:18464
	ds_read_b128 v[154:157], v235 offset:18464
	s_waitcnt lgkmcnt(10)
	v_mfma_f32_32x32x16_bf16 v[34:49], v[162:165], v[174:177], v[34:49]
	ds_read_b128 v[150:153], v234 offset:23072
	ds_read_b128 v[158:161], v235 offset:23072
	v_mfma_f32_32x32x16_bf16 v[50:65], v[166:169], v[174:177], v[50:65]
	s_waitcnt lgkmcnt(10)
	v_mfma_f32_32x32x16_bf16 v[2:17], v[178:181], v[186:189], v[2:17]
	s_waitcnt lgkmcnt(9)
	v_mfma_f32_32x32x16_bf16 v[18:33], v[182:185], v[186:189], v[18:33]
	s_waitcnt lgkmcnt(8)
	v_mfma_f32_32x32x16_bf16 v[34:49], v[178:181], v[190:193], v[34:49]
	v_mfma_f32_32x32x16_bf16 v[50:65], v[182:185], v[190:193], v[50:65]
	s_barrier
	ds_read_b128 v[162:165], v234 offset:18496
	ds_read_b128 v[170:173], v235 offset:18496
	s_waitcnt lgkmcnt(8)
	v_mfma_f32_32x32x16_bf16 v[2:17], v[130:133], v[138:141], v[2:17]
	ds_read_b128 v[166:169], v234 offset:23104
	ds_read_b128 v[174:177], v235 offset:23104
	s_waitcnt lgkmcnt(9)
	v_mfma_f32_32x32x16_bf16 v[18:33], v[134:137], v[138:141], v[18:33]
	ds_read_b128 v[178:181], v234 offset:18528
	ds_read_b128 v[186:189], v235 offset:18528
	s_waitcnt lgkmcnt(10)
	v_mfma_f32_32x32x16_bf16 v[34:49], v[130:133], v[142:145], v[34:49]
	ds_read_b128 v[182:185], v234 offset:23136
	ds_read_b128 v[190:193], v235 offset:23136
	v_mfma_f32_32x32x16_bf16 v[50:65], v[134:137], v[142:145], v[50:65]
	s_waitcnt lgkmcnt(10)
	v_mfma_f32_32x32x16_bf16 v[2:17], v[146:149], v[154:157], v[2:17]
	s_waitcnt lgkmcnt(9)
	v_mfma_f32_32x32x16_bf16 v[18:33], v[150:153], v[154:157], v[18:33]
	s_waitcnt lgkmcnt(8)
	v_mfma_f32_32x32x16_bf16 v[34:49], v[146:149], v[158:161], v[34:49]
	v_mfma_f32_32x32x16_bf16 v[50:65], v[150:153], v[158:161], v[50:65]
	ds_read_b128 v[130:133], v234 offset:36864
	ds_read_b128 v[138:141], v235 offset:36864
	s_waitcnt lgkmcnt(8)
	v_mfma_f32_32x32x16_bf16 v[2:17], v[162:165], v[170:173], v[2:17]
	ds_read_b128 v[134:137], v234 offset:41472
	ds_read_b128 v[142:145], v235 offset:41472
	s_waitcnt lgkmcnt(9)
	v_mfma_f32_32x32x16_bf16 v[18:33], v[166:169], v[170:173], v[18:33]
	ds_read_b128 v[146:149], v234 offset:36896
	ds_read_b128 v[154:157], v235 offset:36896
	s_waitcnt lgkmcnt(10)
	v_mfma_f32_32x32x16_bf16 v[34:49], v[162:165], v[174:177], v[34:49]
	ds_read_b128 v[150:153], v234 offset:41504
	ds_read_b128 v[158:161], v235 offset:41504
	v_mfma_f32_32x32x16_bf16 v[50:65], v[166:169], v[174:177], v[50:65]
	s_waitcnt lgkmcnt(10)
	v_mfma_f32_32x32x16_bf16 v[2:17], v[178:181], v[186:189], v[2:17]
	s_waitcnt lgkmcnt(9)
	v_mfma_f32_32x32x16_bf16 v[18:33], v[182:185], v[186:189], v[18:33]
	s_waitcnt lgkmcnt(8)
	v_mfma_f32_32x32x16_bf16 v[34:49], v[178:181], v[190:193], v[34:49]
	v_mfma_f32_32x32x16_bf16 v[50:65], v[182:185], v[190:193], v[50:65]
	s_waitcnt vmcnt(0)
	s_nop 15
	v_lshlrev_b32_e32 v244, 16, v194
	v_and_b32_e32 v245, 0xffff0000, v194
	v_pk_fma_f32 v[66:67], v[244:245], v[2:3], v[66:67]
	v_lshlrev_b32_e32 v246, 16, v195
	v_and_b32_e32 v247, 0xffff0000, v195
	v_pk_fma_f32 v[68:69], v[246:247], v[4:5], v[68:69]
	v_lshlrev_b32_e32 v248, 16, v196
	v_and_b32_e32 v249, 0xffff0000, v196
	v_pk_fma_f32 v[70:71], v[248:249], v[6:7], v[70:71]
	v_lshlrev_b32_e32 v250, 16, v197
	v_and_b32_e32 v251, 0xffff0000, v197
	v_pk_fma_f32 v[72:73], v[250:251], v[8:9], v[72:73]
	v_lshlrev_b32_e32 v244, 16, v198
	v_and_b32_e32 v245, 0xffff0000, v198
	v_pk_fma_f32 v[74:75], v[244:245], v[10:11], v[74:75]
	v_lshlrev_b32_e32 v246, 16, v199
	v_and_b32_e32 v247, 0xffff0000, v199
	v_pk_fma_f32 v[76:77], v[246:247], v[12:13], v[76:77]
	v_lshlrev_b32_e32 v248, 16, v200
	v_and_b32_e32 v249, 0xffff0000, v200
	v_pk_fma_f32 v[78:79], v[248:249], v[14:15], v[78:79]
	v_lshlrev_b32_e32 v250, 16, v201
	v_and_b32_e32 v251, 0xffff0000, v201
	v_pk_fma_f32 v[80:81], v[250:251], v[16:17], v[80:81]
	v_lshlrev_b32_e32 v244, 16, v202
	v_and_b32_e32 v245, 0xffff0000, v202
	v_pk_fma_f32 v[82:83], v[244:245], v[18:19], v[82:83]
	v_lshlrev_b32_e32 v246, 16, v203
	v_and_b32_e32 v247, 0xffff0000, v203
	v_pk_fma_f32 v[84:85], v[246:247], v[20:21], v[84:85]
	v_lshlrev_b32_e32 v248, 16, v204
	v_and_b32_e32 v249, 0xffff0000, v204
	v_pk_fma_f32 v[86:87], v[248:249], v[22:23], v[86:87]
	v_lshlrev_b32_e32 v250, 16, v205
	v_and_b32_e32 v251, 0xffff0000, v205
; DI float bflo(unsigned w) { return __uint_as_float(w << 16); }
; DI float bfhi(unsigned w) { return __uint_as_float(w & 0xffff0000u); }
; DI f32x16 mfma(bf16x8 a, bf16x8 b, f32x16 c) { return __builtin_amdgcn_mfma_f32_32x32x16_bf16(a, b, c, 0, 0, 0); }
; template <bool RFA, bool RFB, class LA, class LB, class EPI>
; DI void gemm_tile2s(u16* smem, int nk, LA la, LB lb, EPI epi) {
;     ...
;   auto compute = [&](int buf) __attribute__((always_inline)) {
;     const u16* Ab = As + buf * TILE_ELEMS + (wm * 64 + lr) * LDT + lh * 8;
;     const u16* Bb = Bs + buf * TILE_ELEMS + (wn * 32 + lr) * LDT + lh * 8;
; #pragma unroll
;     for (int ks = 0; ks < 4; ++ks) {
;       const bf16x8 a0 = *(const bf16x8*)(Ab + ks * 16);
;       const bf16x8 a1 = *(const bf16x8*)(Ab + 32 * LDT + ks * 16);
;       const bf16x8 b = *(const bf16x8*)(Bb + ks * 16);
;       acc[0] = mfma(a0, b, acc[0]);
;       acc[1] = mfma(a1, b, acc[1]);
;     }
;   };
; template <class ACC>
; DI void merge_branch(const Prm& p, u16* smem, const u16* W, const u16* X, int ld, int bi, int n0, int m0, ACC& macc) {
;     ...
;   auto epi = [&](f32x16 (&acc)[2], int wm, int wn, int lane) __attribute__((always_inline)) {
;     const int lr = lane & 31, lh = lane >> 5;
;     const int tok = m0 + wn * 32 + lr;
; #pragma unroll
;     for (int i = 0; i < 2; ++i)
; #pragma unroll
;       for (int h2 = 0; h2 < 2; ++h2) {
;         const int n = n0 + wm * 64 + i * 32 + 16 * lh + 8 * h2;
;         const u32x4 gz = *(const u32x4*)(p.zg + (size_t)tok * 4096 + bi * 1024 + n);
; #pragma unroll
;         for (int e = 0; e < 4; ++e) {
;           macc[i][8 * h2 + 2 * e] += bflo(gz[e]) * acc[i][8 * h2 + 2 * e];
;           macc[i][8 * h2 + 2 * e + 1] += bfhi(gz[e]) * acc[i][8 * h2 + 2 * e + 1];
;         }
	v_pk_fma_f32 v[88:89], v[250:251], v[24:25], v[88:89]
	v_lshlrev_b32_e32 v244, 16, v206
	v_and_b32_e32 v245, 0xffff0000, v206
	v_pk_fma_f32 v[90:91], v[244:245], v[26:27], v[90:91]
	v_lshlrev_b32_e32 v246, 16, v207
	v_and_b32_e32 v247, 0xffff0000, v207
	v_pk_fma_f32 v[92:93], v[246:247], v[28:29], v[92:93]
	v_lshlrev_b32_e32 v248, 16, v208
	v_and_b32_e32 v249, 0xffff0000, v208
	v_pk_fma_f32 v[94:95], v[248:249], v[30:31], v[94:95]
	v_lshlrev_b32_e32 v250, 16, v209
	v_and_b32_e32 v251, 0xffff0000, v209
	v_pk_fma_f32 v[96:97], v[250:251], v[32:33], v[96:97]
	v_lshlrev_b32_e32 v244, 16, v210
	v_and_b32_e32 v245, 0xffff0000, v210
	v_pk_fma_f32 v[98:99], v[244:245], v[34:35], v[98:99]
	v_lshlrev_b32_e32 v246, 16, v211
	v_and_b32_e32 v247, 0xffff0000, v211
	v_pk_fma_f32 v[100:101], v[246:247], v[36:37], v[100:101]
	v_lshlrev_b32_e32 v248, 16, v212
	v_and_b32_e32 v249, 0xffff0000, v212
	v_pk_fma_f32 v[102:103], v[248:249], v[38:39], v[102:103]
	v_lshlrev_b32_e32 v250, 16, v213
	v_and_b32_e32 v251, 0xffff0000, v213
	v_pk_fma_f32 v[104:105], v[250:251], v[40:41], v[104:105]
	v_lshlrev_b32_e32 v244, 16, v214
	v_and_b32_e32 v245, 0xffff0000, v214
	v_pk_fma_f32 v[106:107], v[244:245], v[42:43], v[106:107]
	v_lshlrev_b32_e32 v246, 16, v215
	v_and_b32_e32 v247, 0xffff0000, v215
	v_pk_fma_f32 v[108:109], v[246:247], v[44:45], v[108:109]
	v_lshlrev_b32_e32 v248, 16, v216
	v_and_b32_e32 v249, 0xffff0000, v216
	v_pk_fma_f32 v[110:111], v[248:249], v[46:47], v[110:111]
	v_lshlrev_b32_e32 v250, 16, v217
	v_and_b32_e32 v251, 0xffff0000, v217
	v_pk_fma_f32 v[112:113], v[250:251], v[48:49], v[112:113]
	v_lshlrev_b32_e32 v244, 16, v218
	v_and_b32_e32 v245, 0xffff0000, v218
	v_pk_fma_f32 v[114:115], v[244:245], v[50:51], v[114:115]
	v_lshlrev_b32_e32 v246, 16, v219
	v_and_b32_e32 v247, 0xffff0000, v219
	v_pk_fma_f32 v[116:117], v[246:247], v[52:53], v[116:117]
	v_lshlrev_b32_e32 v248, 16, v220
	v_and_b32_e32 v249, 0xffff0000, v220
	v_pk_fma_f32 v[118:119], v[248:249], v[54:55], v[118:119]
	v_lshlrev_b32_e32 v250, 16, v221
	v_and_b32_e32 v251, 0xffff0000, v221
	v_pk_fma_f32 v[120:121], v[250:251], v[56:57], v[120:121]
	v_lshlrev_b32_e32 v244, 16, v226
	v_and_b32_e32 v245, 0xffff0000, v226
	v_pk_fma_f32 v[122:123], v[244:245], v[58:59], v[122:123]
	v_lshlrev_b32_e32 v246, 16, v227
	v_and_b32_e32 v247, 0xffff0000, v227
	v_pk_fma_f32 v[124:125], v[246:247], v[60:61], v[124:125]
	v_lshlrev_b32_e32 v248, 16, v228
	v_and_b32_e32 v249, 0xffff0000, v228
	v_pk_fma_f32 v[126:127], v[248:249], v[62:63], v[126:127]
	v_lshlrev_b32_e32 v250, 16, v229
	v_and_b32_e32 v251, 0xffff0000, v229
	v_pk_fma_f32 v[128:129], v[250:251], v[64:65], v[128:129]
	v_add_u32_e32 v244, 0x40000, v236
	global_load_dwordx4 v[194:197], v236, s[10:11] offset:2048
	global_load_dwordx4 v[198:201], v236, s[10:11] offset:2064
	global_load_dwordx4 v[202:205], v236, s[10:11] offset:2112
	global_load_dwordx4 v[206:209], v236, s[10:11] offset:2128
	global_load_dwordx4 v[210:213], v244, s[10:11] offset:2048
	global_load_dwordx4 v[214:217], v244, s[10:11] offset:2064
	global_load_dwordx4 v[218:221], v244, s[10:11] offset:2112
	global_load_dwordx4 v[226:229], v244, s[10:11] offset:2128
	s_barrier
	ds_read_b128 v[162:165], v234 offset:36928
	ds_read_b128 v[170:173], v235 offset:36928
	s_waitcnt lgkmcnt(8)
	v_mfma_f32_32x32x16_bf16 v[2:17], v[130:133], v[138:141], 0
	ds_read_b128 v[166:169], v234 offset:41536
	ds_read_b128 v[174:177], v235 offset:41536
	s_waitcnt lgkmcnt(9)
	v_mfma_f32_32x32x16_bf16 v[18:33], v[134:137], v[138:141], 0
	ds_read_b128 v[178:181], v234 offset:36960
	ds_read_b128 v[186:189], v235 offset:36960
	s_waitcnt lgkmcnt(10)
	v_mfma_f32_32x32x16_bf16 v[34:49], v[130:133], v[142:145], 0
	ds_read_b128 v[182:185], v234 offset:41568
	ds_read_b128 v[190:193], v235 offset:41568
	v_mfma_f32_32x32x16_bf16 v[50:65], v[134:137], v[142:145], 0
	s_waitcnt lgkmcnt(10)
	v_mfma_f32_32x32x16_bf16 v[2:17], v[146:149], v[154:157], v[2:17]
	s_waitcnt lgkmcnt(9)
	v_mfma_f32_32x32x16_bf16 v[18:33], v[150:153], v[154:157], v[18:33]
	s_waitcnt lgkmcnt(8)
	v_mfma_f32_32x32x16_bf16 v[34:49], v[146:149], v[158:161], v[34:49]
	v_mfma_f32_32x32x16_bf16 v[50:65], v[150:153], v[158:161], v[50:65]
	ds_read_b128 v[130:133], v234
	ds_read_b128 v[138:141], v235
	s_waitcnt lgkmcnt(8)
	v_mfma_f32_32x32x16_bf16 v[2:17], v[162:165], v[170:173], v[2:17]
	ds_read_b128 v[134:137], v234 offset:4608
	ds_read_b128 v[142:145], v235 offset:4608
	s_waitcnt lgkmcnt(9)
	v_mfma_f32_32x32x16_bf16 v[18:33], v[166:169], v[170:173], v[18:33]
	ds_read_b128 v[146:149], v234 offset:32
	ds_read_b128 v[154:157], v235 offset:32
	s_waitcnt lgkmcnt(10)
	v_mfma_f32_32x32x16_bf16 v[34:49], v[162:165], v[174:177], v[34:49]
	ds_read_b128 v[150:153], v234 offset:4640
	ds_read_b128 v[158:161], v235 offset:4640
	v_mfma_f32_32x32x16_bf16 v[50:65], v[166:169], v[174:177], v[50:65]
	s_waitcnt lgkmcnt(10)
	v_mfma_f32_32x32x16_bf16 v[2:17], v[178:181], v[186:189], v[2:17]
	s_waitcnt lgkmcnt(9)
	v_mfma_f32_32x32x16_bf16 v[18:33], v[182:185], v[186:189], v[18:33]
	s_waitcnt lgkmcnt(8)
	v_mfma_f32_32x32x16_bf16 v[34:49], v[178:181], v[190:193], v[34:49]
	v_mfma_f32_32x32x16_bf16 v[50:65], v[182:185], v[190:193], v[50:65]
	s_barrier
; DI f32x16 mfma(bf16x8 a, bf16x8 b, f32x16 c) { return __builtin_amdgcn_mfma_f32_32x32x16_bf16(a, b, c, 0, 0, 0); }
; template <bool RFA, bool RFB, class LA, class LB, class EPI>
; DI void gemm_tile2s(u16* smem, int nk, LA la, LB lb, EPI epi) {
;     ...
;   auto compute = [&](int buf) __attribute__((always_inline)) {
;     const u16* Ab = As + buf * TILE_ELEMS + (wm * 64 + lr) * LDT + lh * 8;
;     const u16* Bb = Bs + buf * TILE_ELEMS + (wn * 32 + lr) * LDT + lh * 8;
; #pragma unroll
;     for (int ks = 0; ks < 4; ++ks) {
;       const bf16x8 a0 = *(const bf16x8*)(Ab + ks * 16);
;       const bf16x8 a1 = *(const bf16x8*)(Ab + 32 * LDT + ks * 16);
;       const bf16x8 b = *(const bf16x8*)(Bb + ks * 16);
;       acc[0] = mfma(a0, b, acc[0]);
;       acc[1] = mfma(a1, b, acc[1]);
;     }
;   };
	ds_read_b128 v[162:165], v234 offset:64
	ds_read_b128 v[170:173], v235 offset:64
	s_waitcnt lgkmcnt(8)
	v_mfma_f32_32x32x16_bf16 v[2:17], v[130:133], v[138:141], v[2:17]
	ds_read_b128 v[166:169], v234 offset:4672
	ds_read_b128 v[174:177], v235 offset:4672
	s_waitcnt lgkmcnt(9)
	v_mfma_f32_32x32x16_bf16 v[18:33], v[134:137], v[138:141], v[18:33]
	ds_read_b128 v[178:181], v234 offset:96
	ds_read_b128 v[186:189], v235 offset:96
	s_waitcnt lgkmcnt(10)
	v_mfma_f32_32x32x16_bf16 v[34:49], v[130:133], v[142:145], v[34:49]
	ds_read_b128 v[182:185], v234 offset:4704
	ds_read_b128 v[190:193], v235 offset:4704
	v_mfma_f32_32x32x16_bf16 v[50:65], v[134:137], v[142:145], v[50:65]
	s_waitcnt lgkmcnt(10)
	v_mfma_f32_32x32x16_bf16 v[2:17], v[146:149], v[154:157], v[2:17]
	s_waitcnt lgkmcnt(9)
	v_mfma_f32_32x32x16_bf16 v[18:33], v[150:153], v[154:157], v[18:33]
	s_waitcnt lgkmcnt(8)
	v_mfma_f32_32x32x16_bf16 v[34:49], v[146:149], v[158:161], v[34:49]
	v_mfma_f32_32x32x16_bf16 v[50:65], v[150:153], v[158:161], v[50:65]
	ds_read_b128 v[130:133], v234 offset:18432
	ds_read_b128 v[138:141], v235 offset:18432
	s_waitcnt lgkmcnt(8)
	v_mfma_f32_32x32x16_bf16 v[2:17], v[162:165], v[170:173], v[2:17]
	ds_read_b128 v[134:137], v234 offset:23040
	ds_read_b128 v[142:145], v235 offset:23040
	s_waitcnt lgkmcnt(9)
	v_mfma_f32_32x32x16_bf16 v[18:33], v[166:169], v[170:173], v[18:33]
	ds_read_b128 v[146:149], v234 offset:18464
	ds_read_b128 v[154:157], v235 offset:18464
	s_waitcnt lgkmcnt(10)
	v_mfma_f32_32x32x16_bf16 v[34:49], v[162:165], v[174:177], v[34:49]
	ds_read_b128 v[150:153], v234 offset:23072
	ds_read_b128 v[158:161], v235 offset:23072
	v_mfma_f32_32x32x16_bf16 v[50:65], v[166:169], v[174:177], v[50:65]
	s_waitcnt lgkmcnt(10)
	v_mfma_f32_32x32x16_bf16 v[2:17], v[178:181], v[186:189], v[2:17]
	s_waitcnt lgkmcnt(9)
	v_mfma_f32_32x32x16_bf16 v[18:33], v[182:185], v[186:189], v[18:33]
	s_waitcnt lgkmcnt(8)
	v_mfma_f32_32x32x16_bf16 v[34:49], v[178:181], v[190:193], v[34:49]
	v_mfma_f32_32x32x16_bf16 v[50:65], v[182:185], v[190:193], v[50:65]
	s_barrier
	ds_read_b128 v[162:165], v234 offset:18496
	ds_read_b128 v[170:173], v235 offset:18496
	s_waitcnt lgkmcnt(8)
	v_mfma_f32_32x32x16_bf16 v[2:17], v[130:133], v[138:141], v[2:17]
	ds_read_b128 v[166:169], v234 offset:23104
	ds_read_b128 v[174:177], v235 offset:23104
	s_waitcnt lgkmcnt(9)
	v_mfma_f32_32x32x16_bf16 v[18:33], v[134:137], v[138:141], v[18:33]
	ds_read_b128 v[178:181], v234 offset:18528
	ds_read_b128 v[186:189], v235 offset:18528
	s_waitcnt lgkmcnt(10)
	v_mfma_f32_32x32x16_bf16 v[34:49], v[130:133], v[142:145], v[34:49]
	ds_read_b128 v[182:185], v234 offset:23136
	ds_read_b128 v[190:193], v235 offset:23136
	v_mfma_f32_32x32x16_bf16 v[50:65], v[134:137], v[142:145], v[50:65]
	s_waitcnt lgkmcnt(10)
	v_mfma_f32_32x32x16_bf16 v[2:17], v[146:149], v[154:157], v[2:17]
	s_waitcnt lgkmcnt(9)
	v_mfma_f32_32x32x16_bf16 v[18:33], v[150:153], v[154:157], v[18:33]
	s_waitcnt lgkmcnt(8)
	v_mfma_f32_32x32x16_bf16 v[34:49], v[146:149], v[158:161], v[34:49]
	v_mfma_f32_32x32x16_bf16 v[50:65], v[150:153], v[158:161], v[50:65]
	ds_read_b128 v[130:133], v234 offset:36864
	ds_read_b128 v[138:141], v235 offset:36864
	s_waitcnt lgkmcnt(8)
	v_mfma_f32_32x32x16_bf16 v[2:17], v[162:165], v[170:173], v[2:17]
	ds_read_b128 v[134:137], v234 offset:41472
	ds_read_b128 v[142:145], v235 offset:41472
	s_waitcnt lgkmcnt(9)
	v_mfma_f32_32x32x16_bf16 v[18:33], v[166:169], v[170:173], v[18:33]
	ds_read_b128 v[146:149], v234 offset:36896
	ds_read_b128 v[154:157], v235 offset:36896
	s_waitcnt lgkmcnt(10)
	v_mfma_f32_32x32x16_bf16 v[34:49], v[162:165], v[174:177], v[34:49]
	ds_read_b128 v[150:153], v234 offset:41504
	ds_read_b128 v[158:161], v235 offset:41504
	v_mfma_f32_32x32x16_bf16 v[50:65], v[166:169], v[174:177], v[50:65]
	s_waitcnt lgkmcnt(10)
	v_mfma_f32_32x32x16_bf16 v[2:17], v[178:181], v[186:189], v[2:17]
	s_waitcnt lgkmcnt(9)
	v_mfma_f32_32x32x16_bf16 v[18:33], v[182:185], v[186:189], v[18:33]
	s_waitcnt lgkmcnt(8)
	v_mfma_f32_32x32x16_bf16 v[34:49], v[178:181], v[190:193], v[34:49]
	v_mfma_f32_32x32x16_bf16 v[50:65], v[182:185], v[190:193], v[50:65]
	s_barrier
	ds_read_b128 v[162:165], v234 offset:36928
	ds_read_b128 v[170:173], v235 offset:36928
	s_waitcnt lgkmcnt(8)
	v_mfma_f32_32x32x16_bf16 v[2:17], v[130:133], v[138:141], v[2:17]
	ds_read_b128 v[166:169], v234 offset:41536
	ds_read_b128 v[174:177], v235 offset:41536
	s_waitcnt lgkmcnt(9)
	v_mfma_f32_32x32x16_bf16 v[18:33], v[134:137], v[138:141], v[18:33]
	ds_read_b128 v[178:181], v234 offset:36960
	ds_read_b128 v[186:189], v235 offset:36960
	s_waitcnt lgkmcnt(10)
	v_mfma_f32_32x32x16_bf16 v[34:49], v[130:133], v[142:145], v[34:49]
	ds_read_b128 v[182:185], v234 offset:41568
	ds_read_b128 v[190:193], v235 offset:41568
	v_mfma_f32_32x32x16_bf16 v[50:65], v[134:137], v[142:145], v[50:65]
	s_waitcnt lgkmcnt(10)
	v_mfma_f32_32x32x16_bf16 v[2:17], v[146:149], v[154:157], v[2:17]
	s_waitcnt lgkmcnt(9)
	v_mfma_f32_32x32x16_bf16 v[18:33], v[150:153], v[154:157], v[18:33]
	s_waitcnt lgkmcnt(8)
	v_mfma_f32_32x32x16_bf16 v[34:49], v[146:149], v[158:161], v[34:49]
	v_mfma_f32_32x32x16_bf16 v[50:65], v[150:153], v[158:161], v[50:65]
	ds_read_b128 v[130:133], v234
	ds_read_b128 v[138:141], v235
	s_waitcnt lgkmcnt(8)
	v_mfma_f32_32x32x16_bf16 v[2:17], v[162:165], v[170:173], v[2:17]
	ds_read_b128 v[134:137], v234 offset:4608
	ds_read_b128 v[142:145], v235 offset:4608
	s_waitcnt lgkmcnt(9)
	v_mfma_f32_32x32x16_bf16 v[18:33], v[166:169], v[170:173], v[18:33]
	ds_read_b128 v[146:149], v234 offset:32
	ds_read_b128 v[154:157], v235 offset:32
	s_waitcnt lgkmcnt(10)
; DI float bflo(unsigned w) { return __uint_as_float(w << 16); }
; DI float bfhi(unsigned w) { return __uint_as_float(w & 0xffff0000u); }
; DI int tidx() { int t = threadIdx.x; asm volatile("" : "+v"(t)); return t; }
; #define TASK_LOOP(t, nt, base) for (int t = (int)((blockIdx.x + gridDim.x - ((unsigned)(base) % gridDim.x)) % gridDim.x); t < (nt); t += gridDim.x)
; template <class ACC>
; DI void merge_branch(const Prm& p, u16* smem, const u16* W, const u16* X, int ld, int bi, int n0, int m0, ACC& macc) {
;     ...
;         const u32x4 gz = *(const u32x4*)(p.zg + (size_t)tok * 4096 + bi * 1024 + n);
; #pragma unroll
;         for (int e = 0; e < 4; ++e) {
;           macc[i][8 * h2 + 2 * e] += bflo(gz[e]) * acc[i][8 * h2 + 2 * e];
;           macc[i][8 * h2 + 2 * e + 1] += bfhi(gz[e]) * acc[i][8 * h2 + 2 * e + 1];
;         }
; DI void phase_merge(const Prm& p, u16* smem, int l, int& base) {
;   TASK_LOOP(t, 8 * 128, base) {
;     ...
;     const int tid2 = tidx(), lane = tid2 & 63, wave = tid2 >> 6, wm = wave >> 2, wn = wave & 3, lr = lane & 31, lh = lane >> 5;
;     const int tok = m0 + wn * 32 + lr;
; #pragma unroll
;     for (int i = 0; i < 2; ++i)
; #pragma unroll
;       for (int h2 = 0; h2 < 2; ++h2) {
;         u32x4 o;
; #pragma unroll
;         for (int e = 0; e < 4; ++e) o[e] = pack2(macc[i][8 * h2 + 2 * e], macc[i][8 * h2 + 2 * e + 1]);
;         *(u32x4*)(p.hbuf + (size_t)tok * 1024 + n0 + wm * 64 + i * 32 + 16 * lh + 8 * h2) = o;
;       }
	v_mfma_f32_32x32x16_bf16 v[34:49], v[162:165], v[174:177], v[34:49]
	ds_read_b128 v[150:153], v234 offset:4640
	ds_read_b128 v[158:161], v235 offset:4640
	v_mfma_f32_32x32x16_bf16 v[50:65], v[166:169], v[174:177], v[50:65]
	s_waitcnt lgkmcnt(10)
	v_mfma_f32_32x32x16_bf16 v[2:17], v[178:181], v[186:189], v[2:17]
	s_waitcnt lgkmcnt(9)
	v_mfma_f32_32x32x16_bf16 v[18:33], v[182:185], v[186:189], v[18:33]
	s_waitcnt lgkmcnt(8)
	v_mfma_f32_32x32x16_bf16 v[34:49], v[178:181], v[190:193], v[34:49]
	v_mfma_f32_32x32x16_bf16 v[50:65], v[182:185], v[190:193], v[50:65]
	s_waitcnt vmcnt(0)
	s_nop 15
	v_lshlrev_b32_e32 v244, 16, v194
	v_and_b32_e32 v245, 0xffff0000, v194
	v_pk_fma_f32 v[66:67], v[244:245], v[2:3], v[66:67]
	v_lshlrev_b32_e32 v246, 16, v195
	v_and_b32_e32 v247, 0xffff0000, v195
	v_pk_fma_f32 v[68:69], v[246:247], v[4:5], v[68:69]
	v_lshlrev_b32_e32 v248, 16, v196
	v_and_b32_e32 v249, 0xffff0000, v196
	v_pk_fma_f32 v[70:71], v[248:249], v[6:7], v[70:71]
	v_lshlrev_b32_e32 v250, 16, v197
	v_and_b32_e32 v251, 0xffff0000, v197
	v_pk_fma_f32 v[72:73], v[250:251], v[8:9], v[72:73]
	v_lshlrev_b32_e32 v244, 16, v198
	v_and_b32_e32 v245, 0xffff0000, v198
	v_pk_fma_f32 v[74:75], v[244:245], v[10:11], v[74:75]
	v_lshlrev_b32_e32 v246, 16, v199
	v_and_b32_e32 v247, 0xffff0000, v199
	v_pk_fma_f32 v[76:77], v[246:247], v[12:13], v[76:77]
	v_lshlrev_b32_e32 v248, 16, v200
	v_and_b32_e32 v249, 0xffff0000, v200
	v_pk_fma_f32 v[78:79], v[248:249], v[14:15], v[78:79]
	v_lshlrev_b32_e32 v250, 16, v201
	v_and_b32_e32 v251, 0xffff0000, v201
	v_pk_fma_f32 v[80:81], v[250:251], v[16:17], v[80:81]
	v_lshlrev_b32_e32 v244, 16, v202
	v_and_b32_e32 v245, 0xffff0000, v202
	v_pk_fma_f32 v[82:83], v[244:245], v[18:19], v[82:83]
	v_lshlrev_b32_e32 v246, 16, v203
	v_and_b32_e32 v247, 0xffff0000, v203
	v_pk_fma_f32 v[84:85], v[246:247], v[20:21], v[84:85]
	v_lshlrev_b32_e32 v248, 16, v204
	v_and_b32_e32 v249, 0xffff0000, v204
	v_pk_fma_f32 v[86:87], v[248:249], v[22:23], v[86:87]
	v_lshlrev_b32_e32 v250, 16, v205
	v_and_b32_e32 v251, 0xffff0000, v205
	v_pk_fma_f32 v[88:89], v[250:251], v[24:25], v[88:89]
	v_lshlrev_b32_e32 v244, 16, v206
	v_and_b32_e32 v245, 0xffff0000, v206
	v_pk_fma_f32 v[90:91], v[244:245], v[26:27], v[90:91]
	v_lshlrev_b32_e32 v246, 16, v207
	v_and_b32_e32 v247, 0xffff0000, v207
	v_pk_fma_f32 v[92:93], v[246:247], v[28:29], v[92:93]
	v_lshlrev_b32_e32 v248, 16, v208
	v_and_b32_e32 v249, 0xffff0000, v208
	v_pk_fma_f32 v[94:95], v[248:249], v[30:31], v[94:95]
	v_lshlrev_b32_e32 v250, 16, v209
	v_and_b32_e32 v251, 0xffff0000, v209
	v_pk_fma_f32 v[96:97], v[250:251], v[32:33], v[96:97]
	v_lshlrev_b32_e32 v244, 16, v210
	v_and_b32_e32 v245, 0xffff0000, v210
	v_pk_fma_f32 v[98:99], v[244:245], v[34:35], v[98:99]
	v_lshlrev_b32_e32 v246, 16, v211
	v_and_b32_e32 v247, 0xffff0000, v211
	v_pk_fma_f32 v[100:101], v[246:247], v[36:37], v[100:101]
	v_lshlrev_b32_e32 v248, 16, v212
	v_and_b32_e32 v249, 0xffff0000, v212
	v_pk_fma_f32 v[102:103], v[248:249], v[38:39], v[102:103]
	v_lshlrev_b32_e32 v250, 16, v213
	v_and_b32_e32 v251, 0xffff0000, v213
	v_pk_fma_f32 v[104:105], v[250:251], v[40:41], v[104:105]
	v_lshlrev_b32_e32 v244, 16, v214
	v_and_b32_e32 v245, 0xffff0000, v214
	v_pk_fma_f32 v[106:107], v[244:245], v[42:43], v[106:107]
	v_lshlrev_b32_e32 v246, 16, v215
	v_and_b32_e32 v247, 0xffff0000, v215
	v_pk_fma_f32 v[108:109], v[246:247], v[44:45], v[108:109]
	v_lshlrev_b32_e32 v248, 16, v216
	v_and_b32_e32 v249, 0xffff0000, v216
	v_pk_fma_f32 v[110:111], v[248:249], v[46:47], v[110:111]
	v_lshlrev_b32_e32 v250, 16, v217
	v_and_b32_e32 v251, 0xffff0000, v217
	v_pk_fma_f32 v[112:113], v[250:251], v[48:49], v[112:113]
	v_lshlrev_b32_e32 v244, 16, v218
	v_and_b32_e32 v245, 0xffff0000, v218
	v_pk_fma_f32 v[114:115], v[244:245], v[50:51], v[114:115]
	v_lshlrev_b32_e32 v246, 16, v219
	v_and_b32_e32 v247, 0xffff0000, v219
	v_pk_fma_f32 v[116:117], v[246:247], v[52:53], v[116:117]
	v_lshlrev_b32_e32 v248, 16, v220
	v_and_b32_e32 v249, 0xffff0000, v220
	v_pk_fma_f32 v[118:119], v[248:249], v[54:55], v[118:119]
	v_lshlrev_b32_e32 v250, 16, v221
	v_and_b32_e32 v251, 0xffff0000, v221
	v_pk_fma_f32 v[120:121], v[250:251], v[56:57], v[120:121]
	v_lshlrev_b32_e32 v244, 16, v226
	v_and_b32_e32 v245, 0xffff0000, v226
	v_pk_fma_f32 v[122:123], v[244:245], v[58:59], v[122:123]
	v_lshlrev_b32_e32 v246, 16, v227
	v_and_b32_e32 v247, 0xffff0000, v227
	v_pk_fma_f32 v[124:125], v[246:247], v[60:61], v[124:125]
	v_lshlrev_b32_e32 v248, 16, v228
	v_and_b32_e32 v249, 0xffff0000, v228
	v_pk_fma_f32 v[126:127], v[248:249], v[62:63], v[126:127]
	v_lshlrev_b32_e32 v250, 16, v229
	v_and_b32_e32 v251, 0xffff0000, v229
	v_pk_fma_f32 v[128:129], v[250:251], v[64:65], v[128:129]
	v_cvt_pk_bf16_f32 v194, v66, v67
	v_cvt_pk_bf16_f32 v195, v68, v69
	v_cvt_pk_bf16_f32 v196, v70, v71
	v_cvt_pk_bf16_f32 v197, v72, v73
	v_cvt_pk_bf16_f32 v198, v74, v75
	v_cvt_pk_bf16_f32 v199, v76, v77
	v_cvt_pk_bf16_f32 v200, v78, v79
	v_cvt_pk_bf16_f32 v201, v80, v81
	v_cvt_pk_bf16_f32 v202, v82, v83
	v_cvt_pk_bf16_f32 v203, v84, v85
	v_cvt_pk_bf16_f32 v204, v86, v87
	v_cvt_pk_bf16_f32 v205, v88, v89
	v_cvt_pk_bf16_f32 v206, v90, v91
	v_cvt_pk_bf16_f32 v207, v92, v93
	v_cvt_pk_bf16_f32 v208, v94, v95
	v_cvt_pk_bf16_f32 v209, v96, v97
	v_cvt_pk_bf16_f32 v210, v98, v99
	v_cvt_pk_bf16_f32 v211, v100, v101
	v_cvt_pk_bf16_f32 v212, v102, v103
	v_cvt_pk_bf16_f32 v213, v104, v105
	v_cvt_pk_bf16_f32 v214, v106, v107
	v_cvt_pk_bf16_f32 v215, v108, v109
	v_cvt_pk_bf16_f32 v216, v110, v111
	v_cvt_pk_bf16_f32 v217, v112, v113
	v_cvt_pk_bf16_f32 v218, v114, v115
	v_cvt_pk_bf16_f32 v219, v116, v117
	v_cvt_pk_bf16_f32 v220, v118, v119
	v_cvt_pk_bf16_f32 v221, v120, v121
	v_cvt_pk_bf16_f32 v226, v122, v123
	v_cvt_pk_bf16_f32 v227, v124, v125
	v_cvt_pk_bf16_f32 v228, v126, v127
	v_cvt_pk_bf16_f32 v229, v128, v129
	v_add_u32_e32 v244, 0x10000, v237
	global_store_dwordx4 v237, v[194:197], s[12:13]
	global_store_dwordx4 v237, v[198:201], s[12:13] offset:16
	global_store_dwordx4 v237, v[202:205], s[12:13] offset:64
	global_store_dwordx4 v237, v[206:209], s[12:13] offset:80
	global_store_dwordx4 v244, v[210:213], s[12:13]
	global_store_dwordx4 v244, v[214:217], s[12:13] offset:16
	global_store_dwordx4 v244, v[218:221], s[12:13] offset:64
	global_store_dwordx4 v244, v[226:229], s[12:13] offset:80
	s_barrier
	s_add_i32 s31, s31, s30
	s_cmpk_lt_i32 s31, 0x400
	s_cbranch_scc0 .Lmrgc_end
	s_and_b32 s58, s31, 7
	s_lshl_b32 s58, s58, 7
	s_lshr_b32 s59, s31, 3
	s_lshl_b32 s59, s59, 7
	s_branch .Lmrgc_task
; template <bool RFA, bool RFB, class LA, class LB, class EPI>
; DI void gemm_tile2s(u16* smem, int nk, LA la, LB lb, EPI epi) {
;     ...
;   auto ld = [&](u32x4 (&ra)[2], u32x4 (&rb)[2], int kt) __attribute__((always_inline)) {
;     const int k0 = kt * 64;
; #pragma unroll
;     for (int i = 0; i < 2; ++i) { const int c = tid + NTH * i; ra[i] = la(A_ROW(c), k0 + A_KC(c) * 8); rb[i] = lb(B_ROW(c), k0 + B_KC(c) * 8); }
;   };
;   auto stl = [&](u32x4 (&ra)[2], u32x4 (&rb)[2], int buf) __attribute__((always_inline)) {
; #pragma unroll
;     for (int i = 0; i < 2; ++i) {
;       const int c = tid + NTH * i;
;       *(u32x4*)(As + buf * TILE_ELEMS + A_ROW(c) * LDT + A_KC(c) * 8) = ra[i];
;       *(u32x4*)(Bs + buf * TILE_ELEMS + B_ROW(c) * LDT + B_KC(c) * 8) = rb[i];
;     }
;   };
;     ...
;   ld(ra0, rb0, 0);
;   if (nk > 1) ld(ra1, rb1, 1);
;   stl(ra0, rb0, 0);
;   if (nk > 2) ld(ra0, rb0, 2);
;   __syncthreads();
; template <class ACC>
; DI void merge_branch(const Prm& p, u16* smem, const u16* W, const u16* X, int ld, int bi, int n0, int m0, ACC& macc) {
;   auto la = [&](int row, int k) __attribute__((always_inline)) { return *(const u32x4*)(W + (size_t)(n0 + (row & ~31) + perm_m(row & 31)) * ld + k); };
;   auto lb = [&](int row, int k) __attribute__((always_inline)) { return *(const u32x4*)(X + (size_t)(m0 + row) * ld + k); };
.Lmrgc_end:
	s_waitcnt lgkmcnt(0)
	s_branch .Lmrg_done
.Lmrg_prod:
	v_readlane_b32 s36, v253, 28
	v_readlane_b32 s37, v253, 29
	v_readlane_b32 s38, v253, 30
	v_readlane_b32 s39, v253, 31
	v_readlane_b32 s40, v252, 4
	v_readlane_b32 s41, v252, 5
	v_and_b32_e32 v226, 7, v224
	v_lshlrev_b32_e32 v226, 4, v226
	v_bfe_u32 v227, v224, 3, 5
	v_and_b32_e32 v228, 3, v227
	v_lshrrev_b32_e32 v229, 1, v227
	v_and_b32_e32 v229, 12, v229
	v_or_b32_e32 v228, v228, v229
	v_lshlrev_b32_e32 v229, 2, v227
	v_and_b32_e32 v229, 16, v229
	v_or_b32_e32 v228, v228, v229
	s_movk_i32 s52, 0x600
	v_mad_u32_u24 v130, v228, s52, v226
	v_mad_u32_u24 v134, v227, s52, v226
	s_movk_i32 s52, 0x100
	v_mad_u32_u24 v131, v228, s52, v226
	v_mad_u32_u24 v135, v227, s52, v226
	s_movk_i32 s52, 0x300
	v_mad_u32_u24 v132, v228, s52, v226
	v_mad_u32_u24 v136, v227, s52, v226
	s_movk_i32 s52, 0x200
	v_mad_u32_u24 v133, v228, s52, v226
	v_mad_u32_u24 v137, v227, s52, v226
	s_movk_i32 s52, 0x90
	v_mad_u32_u24 v138, v227, s52, v226
	v_add_u32_e32 v139, 0xd800, v138
	s_and_b32 s58, s31, 7
	s_lshl_b32 s58, s58, 7
	s_lshr_b32 s59, s31, 3
	s_lshl_b32 s59, s59, 7
	s_mul_i32 s52, s58, 0x600
	s_add_u32 s0, s16, s52
	s_addc_u32 s1, s17, 0
	s_add_u32 s2, s0, 0xc000
	s_addc_u32 s3, s1, 0
	s_add_u32 s4, s2, 0xc000
	s_addc_u32 s5, s3, 0
	s_add_u32 s6, s4, 0xc000
	s_addc_u32 s7, s5, 0
	s_mul_i32 s52, s59, 0x600
	s_add_u32 s8, s14, s52
	s_addc_u32 s9, s15, 0
	s_add_u32 s10, s8, 0xc000
	s_addc_u32 s11, s9, 0
	s_add_u32 s12, s10, 0xc000
	s_addc_u32 s13, s11, 0
	s_add_u32 s54, s12, 0xc000
	s_addc_u32 s55, s13, 0
	global_load_dwordx4 v[2:5], v130, s[0:1]
	global_load_dwordx4 v[6:9], v130, s[2:3]
	global_load_dwordx4 v[10:13], v130, s[4:5]
	global_load_dwordx4 v[14:17], v130, s[6:7]
	global_load_dwordx4 v[18:21], v134, s[8:9]
	global_load_dwordx4 v[22:25], v134, s[10:11]
	global_load_dwordx4 v[26:29], v134, s[12:13]
	global_load_dwordx4 v[30:33], v134, s[54:55]
	global_load_dwordx4 v[34:37], v130, s[0:1] offset:128
	global_load_dwordx4 v[38:41], v130, s[2:3] offset:128
	global_load_dwordx4 v[42:45], v130, s[4:5] offset:128
	global_load_dwordx4 v[46:49], v130, s[6:7] offset:128
	global_load_dwordx4 v[50:53], v134, s[8:9] offset:128
	global_load_dwordx4 v[54:57], v134, s[10:11] offset:128
	global_load_dwordx4 v[58:61], v134, s[12:13] offset:128
	global_load_dwordx4 v[62:65], v134, s[54:55] offset:128
	global_load_dwordx4 v[66:69], v130, s[0:1] offset:256
	global_load_dwordx4 v[70:73], v130, s[2:3] offset:256
	global_load_dwordx4 v[74:77], v130, s[4:5] offset:256
	global_load_dwordx4 v[78:81], v130, s[6:7] offset:256
	global_load_dwordx4 v[82:85], v134, s[8:9] offset:256
	global_load_dwordx4 v[86:89], v134, s[10:11] offset:256
	global_load_dwordx4 v[90:93], v134, s[12:13] offset:256
	global_load_dwordx4 v[94:97], v134, s[54:55] offset:256
	global_load_dwordx4 v[98:101], v130, s[0:1] offset:384
	global_load_dwordx4 v[102:105], v130, s[2:3] offset:384
	global_load_dwordx4 v[106:109], v130, s[4:5] offset:384
	global_load_dwordx4 v[110:113], v130, s[6:7] offset:384
	global_load_dwordx4 v[114:117], v134, s[8:9] offset:384
	global_load_dwordx4 v[118:121], v134, s[10:11] offset:384
	global_load_dwordx4 v[122:125], v134, s[12:13] offset:384
	global_load_dwordx4 v[126:129], v134, s[54:55] offset:384
	s_waitcnt vmcnt(16)
	ds_write_b128 v138, v[2:5]
	ds_write_b128 v138, v[6:9] offset:4608
	ds_write_b128 v138, v[10:13] offset:9216
	ds_write_b128 v138, v[14:17] offset:13824
	ds_write_b128 v139, v[18:21]
	ds_write_b128 v139, v[22:25] offset:4608
	ds_write_b128 v139, v[26:29] offset:9216
	ds_write_b128 v139, v[30:33] offset:13824
	ds_write_b128 v138, v[34:37] offset:18432
	ds_write_b128 v138, v[38:41] offset:23040
	ds_write_b128 v138, v[42:45] offset:27648
	ds_write_b128 v138, v[46:49] offset:32256
	ds_write_b128 v139, v[50:53] offset:18432
	ds_write_b128 v139, v[54:57] offset:23040
	ds_write_b128 v139, v[58:61] offset:27648
	ds_write_b128 v139, v[62:65] offset:32256
	global_load_dwordx4 v[2:5], v130, s[0:1] offset:512
	global_load_dwordx4 v[6:9], v130, s[2:3] offset:512
	global_load_dwordx4 v[10:13], v130, s[4:5] offset:512
	global_load_dwordx4 v[14:17], v130, s[6:7] offset:512
	global_load_dwordx4 v[18:21], v134, s[8:9] offset:512
	global_load_dwordx4 v[22:25], v134, s[10:11] offset:512
	global_load_dwordx4 v[26:29], v134, s[12:13] offset:512
	global_load_dwordx4 v[30:33], v134, s[54:55] offset:512
	global_load_dwordx4 v[34:37], v130, s[0:1] offset:640
	global_load_dwordx4 v[38:41], v130, s[2:3] offset:640
	global_load_dwordx4 v[42:45], v130, s[4:5] offset:640
	global_load_dwordx4 v[46:49], v130, s[6:7] offset:640
	global_load_dwordx4 v[50:53], v134, s[8:9] offset:640
	global_load_dwordx4 v[54:57], v134, s[10:11] offset:640
	global_load_dwordx4 v[58:61], v134, s[12:13] offset:640
	global_load_dwordx4 v[62:65], v134, s[54:55] offset:640
	s_waitcnt vmcnt(0)
	s_waitcnt lgkmcnt(0)
	s_barrier
; DI f32x16 zero16() { f32x16 z; for (int i = 0; i < 16; ++i) z[i] = 0.f; return z; }
; #define TASK_LOOP(t, nt, base) for (int t = (int)((blockIdx.x + gridDim.x - ((unsigned)(base) % gridDim.x)) % gridDim.x); t < (nt); t += gridDim.x)
; template <bool RFA, bool RFB, class LA, class LB, class EPI>
; DI void gemm_tile2s(u16* smem, int nk, LA la, LB lb, EPI epi) {
;     ...
;   auto ld = [&](u32x4 (&ra)[2], u32x4 (&rb)[2], int kt) __attribute__((always_inline)) {
;     const int k0 = kt * 64;
; #pragma unroll
;     for (int i = 0; i < 2; ++i) { const int c = tid + NTH * i; ra[i] = la(A_ROW(c), k0 + A_KC(c) * 8); rb[i] = lb(B_ROW(c), k0 + B_KC(c) * 8); }
;   };
;   auto stl = [&](u32x4 (&ra)[2], u32x4 (&rb)[2], int buf) __attribute__((always_inline)) {
; #pragma unroll
;     for (int i = 0; i < 2; ++i) {
;       const int c = tid + NTH * i;
;       *(u32x4*)(As + buf * TILE_ELEMS + A_ROW(c) * LDT + A_KC(c) * 8) = ra[i];
;       *(u32x4*)(Bs + buf * TILE_ELEMS + B_ROW(c) * LDT + B_KC(c) * 8) = rb[i];
;     }
;   };
; DI void phase_merge(const Prm& p, u16* smem, int l, int& base) {
;   TASK_LOOP(t, 8 * 128, base) {
;     const int tn = t & 7, tm = t >> 3, n0 = tn * 128, m0 = tm * 128;
;     f32x16 macc[2];
;     macc[0] = zero16(); macc[1] = zero16();
;     merge_branch(p, smem, p.PaT + (size_t)l * 1024 * 768, p.UT, 768, 0, n0, m0, macc);
;     merge_branch(p, smem, p.PbT + (size_t)l * 1024 * 128, p.ob, 128, 1, n0, m0, macc);
;     ...
;     merge_branch(p, smem, p.PdT + (size_t)l * 1024 * 256, p.od, 256, 3, n0, m0, macc);
.Lmrgp_task:
	s_waitcnt vmcnt(24)
	ds_write_b128 v138, v[66:69] offset:36864
	ds_write_b128 v138, v[70:73] offset:41472
	ds_write_b128 v138, v[74:77] offset:46080
	ds_write_b128 v138, v[78:81] offset:50688
	ds_write_b128 v139, v[82:85] offset:36864
	ds_write_b128 v139, v[86:89] offset:41472
	ds_write_b128 v139, v[90:93] offset:46080
	ds_write_b128 v139, v[94:97] offset:50688
	global_load_dwordx4 v[66:69], v130, s[0:1] offset:768
	global_load_dwordx4 v[70:73], v130, s[2:3] offset:768
	global_load_dwordx4 v[74:77], v130, s[4:5] offset:768
	global_load_dwordx4 v[78:81], v130, s[6:7] offset:768
	global_load_dwordx4 v[82:85], v134, s[8:9] offset:768
	global_load_dwordx4 v[86:89], v134, s[10:11] offset:768
	global_load_dwordx4 v[90:93], v134, s[12:13] offset:768
	global_load_dwordx4 v[94:97], v134, s[54:55] offset:768
	s_waitcnt lgkmcnt(0)
	s_barrier
	s_waitcnt vmcnt(24)
	ds_write_b128 v138, v[98:101]
	ds_write_b128 v138, v[102:105] offset:4608
	ds_write_b128 v138, v[106:109] offset:9216
	ds_write_b128 v138, v[110:113] offset:13824
	ds_write_b128 v139, v[114:117]
	ds_write_b128 v139, v[118:121] offset:4608
	ds_write_b128 v139, v[122:125] offset:9216
	ds_write_b128 v139, v[126:129] offset:13824
	global_load_dwordx4 v[98:101], v130, s[0:1] offset:896
	global_load_dwordx4 v[102:105], v130, s[2:3] offset:896
	global_load_dwordx4 v[106:109], v130, s[4:5] offset:896
	global_load_dwordx4 v[110:113], v130, s[6:7] offset:896
	global_load_dwordx4 v[114:117], v134, s[8:9] offset:896
	global_load_dwordx4 v[118:121], v134, s[10:11] offset:896
	global_load_dwordx4 v[122:125], v134, s[12:13] offset:896
	global_load_dwordx4 v[126:129], v134, s[54:55] offset:896
	s_waitcnt lgkmcnt(0)
	s_barrier
	s_waitcnt vmcnt(24)
	ds_write_b128 v138, v[2:5] offset:18432
	ds_write_b128 v138, v[6:9] offset:23040
	ds_write_b128 v138, v[10:13] offset:27648
	ds_write_b128 v138, v[14:17] offset:32256
	ds_write_b128 v139, v[18:21] offset:18432
	ds_write_b128 v139, v[22:25] offset:23040
	ds_write_b128 v139, v[26:29] offset:27648
	ds_write_b128 v139, v[30:33] offset:32256
	global_load_dwordx4 v[2:5], v130, s[0:1] offset:1024
	global_load_dwordx4 v[6:9], v130, s[2:3] offset:1024
	global_load_dwordx4 v[10:13], v130, s[4:5] offset:1024
	global_load_dwordx4 v[14:17], v130, s[6:7] offset:1024
	global_load_dwordx4 v[18:21], v134, s[8:9] offset:1024
	global_load_dwordx4 v[22:25], v134, s[10:11] offset:1024
	global_load_dwordx4 v[26:29], v134, s[12:13] offset:1024
	global_load_dwordx4 v[30:33], v134, s[54:55] offset:1024
	s_waitcnt lgkmcnt(0)
	s_barrier
	s_waitcnt vmcnt(24)
	ds_write_b128 v138, v[34:37] offset:36864
	ds_write_b128 v138, v[38:41] offset:41472
	ds_write_b128 v138, v[42:45] offset:46080
	ds_write_b128 v138, v[46:49] offset:50688
	ds_write_b128 v139, v[50:53] offset:36864
	ds_write_b128 v139, v[54:57] offset:41472
	ds_write_b128 v139, v[58:61] offset:46080
	ds_write_b128 v139, v[62:65] offset:50688
	global_load_dwordx4 v[34:37], v130, s[0:1] offset:1152
	global_load_dwordx4 v[38:41], v130, s[2:3] offset:1152
	global_load_dwordx4 v[42:45], v130, s[4:5] offset:1152
	global_load_dwordx4 v[46:49], v130, s[6:7] offset:1152
	global_load_dwordx4 v[50:53], v134, s[8:9] offset:1152
	global_load_dwordx4 v[54:57], v134, s[10:11] offset:1152
	global_load_dwordx4 v[58:61], v134, s[12:13] offset:1152
	global_load_dwordx4 v[62:65], v134, s[54:55] offset:1152
	s_waitcnt lgkmcnt(0)
	s_barrier
	s_waitcnt vmcnt(24)
	ds_write_b128 v138, v[66:69]
	ds_write_b128 v138, v[70:73] offset:4608
	ds_write_b128 v138, v[74:77] offset:9216
	ds_write_b128 v138, v[78:81] offset:13824
	ds_write_b128 v139, v[82:85]
	ds_write_b128 v139, v[86:89] offset:4608
	ds_write_b128 v139, v[90:93] offset:9216
	ds_write_b128 v139, v[94:97] offset:13824
	global_load_dwordx4 v[66:69], v130, s[0:1] offset:1280
	global_load_dwordx4 v[70:73], v130, s[2:3] offset:1280
	global_load_dwordx4 v[74:77], v130, s[4:5] offset:1280
	global_load_dwordx4 v[78:81], v130, s[6:7] offset:1280
	global_load_dwordx4 v[82:85], v134, s[8:9] offset:1280
	global_load_dwordx4 v[86:89], v134, s[10:11] offset:1280
	global_load_dwordx4 v[90:93], v134, s[12:13] offset:1280
	global_load_dwordx4 v[94:97], v134, s[54:55] offset:1280
	s_waitcnt lgkmcnt(0)
	s_barrier
	s_waitcnt vmcnt(24)
	ds_write_b128 v138, v[98:101] offset:18432
	ds_write_b128 v138, v[102:105] offset:23040
	ds_write_b128 v138, v[106:109] offset:27648
	ds_write_b128 v138, v[110:113] offset:32256
	ds_write_b128 v139, v[114:117] offset:18432
	ds_write_b128 v139, v[118:121] offset:23040
	ds_write_b128 v139, v[122:125] offset:27648
	ds_write_b128 v139, v[126:129] offset:32256
	global_load_dwordx4 v[98:101], v130, s[0:1] offset:1408
	global_load_dwordx4 v[102:105], v130, s[2:3] offset:1408
	global_load_dwordx4 v[106:109], v130, s[4:5] offset:1408
	global_load_dwordx4 v[110:113], v130, s[6:7] offset:1408
	global_load_dwordx4 v[114:117], v134, s[8:9] offset:1408
	global_load_dwordx4 v[118:121], v134, s[10:11] offset:1408
	global_load_dwordx4 v[122:125], v134, s[12:13] offset:1408
	global_load_dwordx4 v[126:129], v134, s[54:55] offset:1408
	s_waitcnt lgkmcnt(0)
	s_barrier
; DI f32x16 zero16() { f32x16 z; for (int i = 0; i < 16; ++i) z[i] = 0.f; return z; }
; #define TASK_LOOP(t, nt, base) for (int t = (int)((blockIdx.x + gridDim.x - ((unsigned)(base) % gridDim.x)) % gridDim.x); t < (nt); t += gridDim.x)
; template <bool RFA, bool RFB, class LA, class LB, class EPI>
; DI void gemm_tile2s(u16* smem, int nk, LA la, LB lb, EPI epi) {
;     ...
;   auto ld = [&](u32x4 (&ra)[2], u32x4 (&rb)[2], int kt) __attribute__((always_inline)) {
;     const int k0 = kt * 64;
; #pragma unroll
;     for (int i = 0; i < 2; ++i) { const int c = tid + NTH * i; ra[i] = la(A_ROW(c), k0 + A_KC(c) * 8); rb[i] = lb(B_ROW(c), k0 + B_KC(c) * 8); }
;   };
;   auto stl = [&](u32x4 (&ra)[2], u32x4 (&rb)[2], int buf) __attribute__((always_inline)) {
; #pragma unroll
;     for (int i = 0; i < 2; ++i) {
;       const int c = tid + NTH * i;
;       *(u32x4*)(As + buf * TILE_ELEMS + A_ROW(c) * LDT + A_KC(c) * 8) = ra[i];
;       *(u32x4*)(Bs + buf * TILE_ELEMS + B_ROW(c) * LDT + B_KC(c) * 8) = rb[i];
;     }
;   };
; DI void phase_merge(const Prm& p, u16* smem, int l, int& base) {
;   TASK_LOOP(t, 8 * 128, base) {
;     const int tn = t & 7, tm = t >> 3, n0 = tn * 128, m0 = tm * 128;
;     f32x16 macc[2];
;     macc[0] = zero16(); macc[1] = zero16();
;     merge_branch(p, smem, p.PaT + (size_t)l * 1024 * 768, p.UT, 768, 0, n0, m0, macc);
;     merge_branch(p, smem, p.PbT + (size_t)l * 1024 * 128, p.ob, 128, 1, n0, m0, macc);
;     ...
;     merge_branch(p, smem, p.PdT + (size_t)l * 1024 * 256, p.od, 256, 3, n0, m0, macc);
	s_waitcnt vmcnt(24)
	ds_write_b128 v138, v[2:5] offset:36864
	ds_write_b128 v138, v[6:9] offset:41472
	ds_write_b128 v138, v[10:13] offset:46080
	ds_write_b128 v138, v[14:17] offset:50688
	ds_write_b128 v139, v[18:21] offset:36864
	ds_write_b128 v139, v[22:25] offset:41472
	ds_write_b128 v139, v[26:29] offset:46080
	ds_write_b128 v139, v[30:33] offset:50688
	s_mul_i32 s52, s58, 0x100
	s_add_u32 s0, s20, s52
	s_addc_u32 s1, s21, 0
	s_add_u32 s2, s0, 0x2000
	s_addc_u32 s3, s1, 0
	s_add_u32 s4, s2, 0x2000
	s_addc_u32 s5, s3, 0
	s_add_u32 s6, s4, 0x2000
	s_addc_u32 s7, s5, 0
	s_mul_i32 s52, s59, 0x100
	s_add_u32 s8, s36, s52
	s_addc_u32 s9, s37, 0
	s_add_u32 s10, s8, 0x2000
	s_addc_u32 s11, s9, 0
	s_add_u32 s12, s10, 0x2000
	s_addc_u32 s13, s11, 0
	s_add_u32 s54, s12, 0x2000
	s_addc_u32 s55, s13, 0
	global_load_dwordx4 v[2:5], v131, s[0:1]
	global_load_dwordx4 v[6:9], v131, s[2:3]
	global_load_dwordx4 v[10:13], v131, s[4:5]
	global_load_dwordx4 v[14:17], v131, s[6:7]
	global_load_dwordx4 v[18:21], v135, s[8:9]
	global_load_dwordx4 v[22:25], v135, s[10:11]
	global_load_dwordx4 v[26:29], v135, s[12:13]
	global_load_dwordx4 v[30:33], v135, s[54:55]
	s_waitcnt lgkmcnt(0)
	s_barrier
	s_waitcnt vmcnt(24)
	ds_write_b128 v138, v[34:37]
	ds_write_b128 v138, v[38:41] offset:4608
	ds_write_b128 v138, v[42:45] offset:9216
	ds_write_b128 v138, v[46:49] offset:13824
	ds_write_b128 v139, v[50:53]
	ds_write_b128 v139, v[54:57] offset:4608
	ds_write_b128 v139, v[58:61] offset:9216
	ds_write_b128 v139, v[62:65] offset:13824
	global_load_dwordx4 v[34:37], v131, s[0:1] offset:128
	global_load_dwordx4 v[38:41], v131, s[2:3] offset:128
	global_load_dwordx4 v[42:45], v131, s[4:5] offset:128
	global_load_dwordx4 v[46:49], v131, s[6:7] offset:128
	global_load_dwordx4 v[50:53], v135, s[8:9] offset:128
	global_load_dwordx4 v[54:57], v135, s[10:11] offset:128
	global_load_dwordx4 v[58:61], v135, s[12:13] offset:128
	global_load_dwordx4 v[62:65], v135, s[54:55] offset:128
	s_waitcnt lgkmcnt(0)
	s_barrier
	s_waitcnt vmcnt(24)
	ds_write_b128 v138, v[66:69] offset:18432
	ds_write_b128 v138, v[70:73] offset:23040
	ds_write_b128 v138, v[74:77] offset:27648
	ds_write_b128 v138, v[78:81] offset:32256
	ds_write_b128 v139, v[82:85] offset:18432
	ds_write_b128 v139, v[86:89] offset:23040
	ds_write_b128 v139, v[90:93] offset:27648
	ds_write_b128 v139, v[94:97] offset:32256
	s_mul_i32 s52, s58, 0x300
	s_add_u32 s0, s22, s52
	s_addc_u32 s1, s23, 0
	s_add_u32 s2, s0, 0x6000
	s_addc_u32 s3, s1, 0
	s_add_u32 s4, s2, 0x6000
	s_addc_u32 s5, s3, 0
	s_add_u32 s6, s4, 0x6000
	s_addc_u32 s7, s5, 0
	s_mul_i32 s52, s59, 0x300
	s_add_u32 s8, s38, s52
	s_addc_u32 s9, s39, 0
	s_add_u32 s10, s8, 0x6000
	s_addc_u32 s11, s9, 0
	s_add_u32 s12, s10, 0x6000
	s_addc_u32 s13, s11, 0
	s_add_u32 s54, s12, 0x6000
	s_addc_u32 s55, s13, 0
	global_load_dwordx4 v[66:69], v132, s[0:1]
	global_load_dwordx4 v[70:73], v132, s[2:3]
	global_load_dwordx4 v[74:77], v132, s[4:5]
	global_load_dwordx4 v[78:81], v132, s[6:7]
	global_load_dwordx4 v[82:85], v136, s[8:9]
	global_load_dwordx4 v[86:89], v136, s[10:11]
	global_load_dwordx4 v[90:93], v136, s[12:13]
	global_load_dwordx4 v[94:97], v136, s[54:55]
	s_waitcnt lgkmcnt(0)
	s_barrier
	s_waitcnt vmcnt(24)
	ds_write_b128 v138, v[98:101] offset:36864
	ds_write_b128 v138, v[102:105] offset:41472
	ds_write_b128 v138, v[106:109] offset:46080
	ds_write_b128 v138, v[110:113] offset:50688
	ds_write_b128 v139, v[114:117] offset:36864
	ds_write_b128 v139, v[118:121] offset:41472
	ds_write_b128 v139, v[122:125] offset:46080
	ds_write_b128 v139, v[126:129] offset:50688
	global_load_dwordx4 v[98:101], v132, s[0:1] offset:128
	global_load_dwordx4 v[102:105], v132, s[2:3] offset:128
	global_load_dwordx4 v[106:109], v132, s[4:5] offset:128
	global_load_dwordx4 v[110:113], v132, s[6:7] offset:128
	global_load_dwordx4 v[114:117], v136, s[8:9] offset:128
	global_load_dwordx4 v[118:121], v136, s[10:11] offset:128
	global_load_dwordx4 v[122:125], v136, s[12:13] offset:128
	global_load_dwordx4 v[126:129], v136, s[54:55] offset:128
	s_waitcnt lgkmcnt(0)
	s_barrier
	s_waitcnt vmcnt(24)
	ds_write_b128 v138, v[2:5]
	ds_write_b128 v138, v[6:9] offset:4608
	ds_write_b128 v138, v[10:13] offset:9216
	ds_write_b128 v138, v[14:17] offset:13824
	ds_write_b128 v139, v[18:21]
	ds_write_b128 v139, v[22:25] offset:4608
	ds_write_b128 v139, v[26:29] offset:9216
	ds_write_b128 v139, v[30:33] offset:13824
	global_load_dwordx4 v[2:5], v132, s[0:1] offset:256
	global_load_dwordx4 v[6:9], v132, s[2:3] offset:256
	global_load_dwordx4 v[10:13], v132, s[4:5] offset:256
	global_load_dwordx4 v[14:17], v132, s[6:7] offset:256
	global_load_dwordx4 v[18:21], v136, s[8:9] offset:256
	global_load_dwordx4 v[22:25], v136, s[10:11] offset:256
	global_load_dwordx4 v[26:29], v136, s[12:13] offset:256
	global_load_dwordx4 v[30:33], v136, s[54:55] offset:256
	s_waitcnt lgkmcnt(0)
	s_barrier
	s_waitcnt vmcnt(24)
	ds_write_b128 v138, v[34:37] offset:18432
	ds_write_b128 v138, v[38:41] offset:23040
	ds_write_b128 v138, v[42:45] offset:27648
	ds_write_b128 v138, v[46:49] offset:32256
	ds_write_b128 v139, v[50:53] offset:18432
	ds_write_b128 v139, v[54:57] offset:23040
	ds_write_b128 v139, v[58:61] offset:27648
	ds_write_b128 v139, v[62:65] offset:32256
	global_load_dwordx4 v[34:37], v132, s[0:1] offset:384
	global_load_dwordx4 v[38:41], v132, s[2:3] offset:384
	global_load_dwordx4 v[42:45], v132, s[4:5] offset:384
	global_load_dwordx4 v[46:49], v132, s[6:7] offset:384
	global_load_dwordx4 v[50:53], v136, s[8:9] offset:384
	global_load_dwordx4 v[54:57], v136, s[10:11] offset:384
	global_load_dwordx4 v[58:61], v136, s[12:13] offset:384
	global_load_dwordx4 v[62:65], v136, s[54:55] offset:384
	s_waitcnt lgkmcnt(0)
	s_barrier
; DI f32x16 zero16() { f32x16 z; for (int i = 0; i < 16; ++i) z[i] = 0.f; return z; }
; #define TASK_LOOP(t, nt, base) for (int t = (int)((blockIdx.x + gridDim.x - ((unsigned)(base) % gridDim.x)) % gridDim.x); t < (nt); t += gridDim.x)
; template <bool RFA, bool RFB, class LA, class LB, class EPI>
; DI void gemm_tile2s(u16* smem, int nk, LA la, LB lb, EPI epi) {
;     ...
;   auto ld = [&](u32x4 (&ra)[2], u32x4 (&rb)[2], int kt) __attribute__((always_inline)) {
;     const int k0 = kt * 64;
; #pragma unroll
;     for (int i = 0; i < 2; ++i) { const int c = tid + NTH * i; ra[i] = la(A_ROW(c), k0 + A_KC(c) * 8); rb[i] = lb(B_ROW(c), k0 + B_KC(c) * 8); }
;   };
;   auto stl = [&](u32x4 (&ra)[2], u32x4 (&rb)[2], int buf) __attribute__((always_inline)) {
; #pragma unroll
;     for (int i = 0; i < 2; ++i) {
;       const int c = tid + NTH * i;
;       *(u32x4*)(As + buf * TILE_ELEMS + A_ROW(c) * LDT + A_KC(c) * 8) = ra[i];
;       *(u32x4*)(Bs + buf * TILE_ELEMS + B_ROW(c) * LDT + B_KC(c) * 8) = rb[i];
;     }
;   };
; DI void phase_merge(const Prm& p, u16* smem, int l, int& base) {
;   TASK_LOOP(t, 8 * 128, base) {
;     const int tn = t & 7, tm = t >> 3, n0 = tn * 128, m0 = tm * 128;
;     f32x16 macc[2];
;     macc[0] = zero16(); macc[1] = zero16();
;     merge_branch(p, smem, p.PaT + (size_t)l * 1024 * 768, p.UT, 768, 0, n0, m0, macc);
;     merge_branch(p, smem, p.PbT + (size_t)l * 1024 * 128, p.ob, 128, 1, n0, m0, macc);
;     ...
;     merge_branch(p, smem, p.PdT + (size_t)l * 1024 * 256, p.od, 256, 3, n0, m0, macc);
	s_waitcnt vmcnt(24)
	ds_write_b128 v138, v[66:69] offset:36864
	ds_write_b128 v138, v[70:73] offset:41472
	ds_write_b128 v138, v[74:77] offset:46080
	ds_write_b128 v138, v[78:81] offset:50688
	ds_write_b128 v139, v[82:85] offset:36864
	ds_write_b128 v139, v[86:89] offset:41472
	ds_write_b128 v139, v[90:93] offset:46080
	ds_write_b128 v139, v[94:97] offset:50688
	global_load_dwordx4 v[66:69], v132, s[0:1] offset:512
	global_load_dwordx4 v[70:73], v132, s[2:3] offset:512
	global_load_dwordx4 v[74:77], v132, s[4:5] offset:512
	global_load_dwordx4 v[78:81], v132, s[6:7] offset:512
	global_load_dwordx4 v[82:85], v136, s[8:9] offset:512
	global_load_dwordx4 v[86:89], v136, s[10:11] offset:512
	global_load_dwordx4 v[90:93], v136, s[12:13] offset:512
	global_load_dwordx4 v[94:97], v136, s[54:55] offset:512
	s_waitcnt lgkmcnt(0)
	s_barrier
	s_waitcnt vmcnt(24)
	ds_write_b128 v138, v[98:101]
	ds_write_b128 v138, v[102:105] offset:4608
	ds_write_b128 v138, v[106:109] offset:9216
	ds_write_b128 v138, v[110:113] offset:13824
	ds_write_b128 v139, v[114:117]
	ds_write_b128 v139, v[118:121] offset:4608
	ds_write_b128 v139, v[122:125] offset:9216
	ds_write_b128 v139, v[126:129] offset:13824
	global_load_dwordx4 v[98:101], v132, s[0:1] offset:640
	global_load_dwordx4 v[102:105], v132, s[2:3] offset:640
	global_load_dwordx4 v[106:109], v132, s[4:5] offset:640
	global_load_dwordx4 v[110:113], v132, s[6:7] offset:640
	global_load_dwordx4 v[114:117], v136, s[8:9] offset:640
	global_load_dwordx4 v[118:121], v136, s[10:11] offset:640
	global_load_dwordx4 v[122:125], v136, s[12:13] offset:640
	global_load_dwordx4 v[126:129], v136, s[54:55] offset:640
	s_waitcnt lgkmcnt(0)
	s_barrier
	s_waitcnt vmcnt(24)
	ds_write_b128 v138, v[2:5] offset:18432
	ds_write_b128 v138, v[6:9] offset:23040
	ds_write_b128 v138, v[10:13] offset:27648
	ds_write_b128 v138, v[14:17] offset:32256
	ds_write_b128 v139, v[18:21] offset:18432
	ds_write_b128 v139, v[22:25] offset:23040
	ds_write_b128 v139, v[26:29] offset:27648
	ds_write_b128 v139, v[30:33] offset:32256
	s_mul_i32 s52, s58, 0x200
	s_add_u32 s0, s44, s52
	s_addc_u32 s1, s45, 0
	s_add_u32 s2, s0, 0x4000
	s_addc_u32 s3, s1, 0
	s_add_u32 s4, s2, 0x4000
	s_addc_u32 s5, s3, 0
	s_add_u32 s6, s4, 0x4000
	s_addc_u32 s7, s5, 0
	s_mul_i32 s52, s59, 0x200
	s_add_u32 s8, s40, s52
	s_addc_u32 s9, s41, 0
	s_add_u32 s10, s8, 0x4000
	s_addc_u32 s11, s9, 0
	s_add_u32 s12, s10, 0x4000
	s_addc_u32 s13, s11, 0
	s_add_u32 s54, s12, 0x4000
	s_addc_u32 s55, s13, 0
	global_load_dwordx4 v[2:5], v133, s[0:1]
	global_load_dwordx4 v[6:9], v133, s[2:3]
	global_load_dwordx4 v[10:13], v133, s[4:5]
	global_load_dwordx4 v[14:17], v133, s[6:7]
	global_load_dwordx4 v[18:21], v137, s[8:9]
	global_load_dwordx4 v[22:25], v137, s[10:11]
	global_load_dwordx4 v[26:29], v137, s[12:13]
	global_load_dwordx4 v[30:33], v137, s[54:55]
	s_waitcnt lgkmcnt(0)
	s_barrier
	s_waitcnt vmcnt(24)
	ds_write_b128 v138, v[34:37] offset:36864
	ds_write_b128 v138, v[38:41] offset:41472
	ds_write_b128 v138, v[42:45] offset:46080
	ds_write_b128 v138, v[46:49] offset:50688
	ds_write_b128 v139, v[50:53] offset:36864
	ds_write_b128 v139, v[54:57] offset:41472
	ds_write_b128 v139, v[58:61] offset:46080
	ds_write_b128 v139, v[62:65] offset:50688
	global_load_dwordx4 v[34:37], v133, s[0:1] offset:128
	global_load_dwordx4 v[38:41], v133, s[2:3] offset:128
	global_load_dwordx4 v[42:45], v133, s[4:5] offset:128
	global_load_dwordx4 v[46:49], v133, s[6:7] offset:128
	global_load_dwordx4 v[50:53], v137, s[8:9] offset:128
	global_load_dwordx4 v[54:57], v137, s[10:11] offset:128
	global_load_dwordx4 v[58:61], v137, s[12:13] offset:128
	global_load_dwordx4 v[62:65], v137, s[54:55] offset:128
	s_waitcnt lgkmcnt(0)
	s_barrier
	s_waitcnt vmcnt(24)
	ds_write_b128 v138, v[66:69]
	ds_write_b128 v138, v[70:73] offset:4608
	ds_write_b128 v138, v[74:77] offset:9216
	ds_write_b128 v138, v[78:81] offset:13824
	ds_write_b128 v139, v[82:85]
	ds_write_b128 v139, v[86:89] offset:4608
	ds_write_b128 v139, v[90:93] offset:9216
	ds_write_b128 v139, v[94:97] offset:13824
	global_load_dwordx4 v[66:69], v133, s[0:1] offset:256
	global_load_dwordx4 v[70:73], v133, s[2:3] offset:256
	global_load_dwordx4 v[74:77], v133, s[4:5] offset:256
	global_load_dwordx4 v[78:81], v133, s[6:7] offset:256
	global_load_dwordx4 v[82:85], v137, s[8:9] offset:256
	global_load_dwordx4 v[86:89], v137, s[10:11] offset:256
	global_load_dwordx4 v[90:93], v137, s[12:13] offset:256
	global_load_dwordx4 v[94:97], v137, s[54:55] offset:256
	s_waitcnt lgkmcnt(0)
	s_barrier
	s_waitcnt vmcnt(24)
	ds_write_b128 v138, v[98:101] offset:18432
	ds_write_b128 v138, v[102:105] offset:23040
	ds_write_b128 v138, v[106:109] offset:27648
	ds_write_b128 v138, v[110:113] offset:32256
	ds_write_b128 v139, v[114:117] offset:18432
	ds_write_b128 v139, v[118:121] offset:23040
	ds_write_b128 v139, v[122:125] offset:27648
	ds_write_b128 v139, v[126:129] offset:32256
	global_load_dwordx4 v[98:101], v133, s[0:1] offset:384
	global_load_dwordx4 v[102:105], v133, s[2:3] offset:384
	global_load_dwordx4 v[106:109], v133, s[4:5] offset:384
	global_load_dwordx4 v[110:113], v133, s[6:7] offset:384
	global_load_dwordx4 v[114:117], v137, s[8:9] offset:384
	global_load_dwordx4 v[118:121], v137, s[10:11] offset:384
	global_load_dwordx4 v[122:125], v137, s[12:13] offset:384
	global_load_dwordx4 v[126:129], v137, s[54:55] offset:384
	s_waitcnt lgkmcnt(0)
	s_barrier
; DI f32x16 zero16() { f32x16 z; for (int i = 0; i < 16; ++i) z[i] = 0.f; return z; }
; #define TASK_LOOP(t, nt, base) for (int t = (int)((blockIdx.x + gridDim.x - ((unsigned)(base) % gridDim.x)) % gridDim.x); t < (nt); t += gridDim.x)
; template <bool RFA, bool RFB, class LA, class LB, class EPI>
; DI void gemm_tile2s(u16* smem, int nk, LA la, LB lb, EPI epi) {
;     ...
;   auto ld = [&](u32x4 (&ra)[2], u32x4 (&rb)[2], int kt) __attribute__((always_inline)) {
;     const int k0 = kt * 64;
; #pragma unroll
;     for (int i = 0; i < 2; ++i) { const int c = tid + NTH * i; ra[i] = la(A_ROW(c), k0 + A_KC(c) * 8); rb[i] = lb(B_ROW(c), k0 + B_KC(c) * 8); }
;   };
;   auto stl = [&](u32x4 (&ra)[2], u32x4 (&rb)[2], int buf) __attribute__((always_inline)) {
; #pragma unroll
;     for (int i = 0; i < 2; ++i) {
;       const int c = tid + NTH * i;
;       *(u32x4*)(As + buf * TILE_ELEMS + A_ROW(c) * LDT + A_KC(c) * 8) = ra[i];
;       *(u32x4*)(Bs + buf * TILE_ELEMS + B_ROW(c) * LDT + B_KC(c) * 8) = rb[i];
;     }
;   };
; DI void phase_merge(const Prm& p, u16* smem, int l, int& base) {
;   TASK_LOOP(t, 8 * 128, base) {
;     const int tn = t & 7, tm = t >> 3, n0 = tn * 128, m0 = tm * 128;
;     f32x16 macc[2];
;     macc[0] = zero16(); macc[1] = zero16();
;     merge_branch(p, smem, p.PaT + (size_t)l * 1024 * 768, p.UT, 768, 0, n0, m0, macc);
;     merge_branch(p, smem, p.PbT + (size_t)l * 1024 * 128, p.ob, 128, 1, n0, m0, macc);
;     ...
;     merge_branch(p, smem, p.PdT + (size_t)l * 1024 * 256, p.od, 256, 3, n0, m0, macc);
	s_waitcnt vmcnt(24)
	ds_write_b128 v138, v[2:5] offset:36864
	ds_write_b128 v138, v[6:9] offset:41472
	ds_write_b128 v138, v[10:13] offset:46080
	ds_write_b128 v138, v[14:17] offset:50688
	ds_write_b128 v139, v[18:21] offset:36864
	ds_write_b128 v139, v[22:25] offset:41472
	ds_write_b128 v139, v[26:29] offset:46080
	ds_write_b128 v139, v[30:33] offset:50688
	s_add_i32 s50, s31, s30
	s_cmpk_lt_i32 s50, 0x400
	s_cselect_b32 s50, s50, s31
	s_and_b32 s60, s50, 7
	s_lshl_b32 s60, s60, 7
	s_lshr_b32 s61, s50, 3
	s_lshl_b32 s61, s61, 7
	s_mul_i32 s52, s60, 0x600
	s_add_u32 s0, s16, s52
	s_addc_u32 s1, s17, 0
	s_add_u32 s2, s0, 0xc000
	s_addc_u32 s3, s1, 0
	s_add_u32 s4, s2, 0xc000
	s_addc_u32 s5, s3, 0
	s_add_u32 s6, s4, 0xc000
	s_addc_u32 s7, s5, 0
	s_mul_i32 s52, s61, 0x600
	s_add_u32 s8, s14, s52
	s_addc_u32 s9, s15, 0
	s_add_u32 s10, s8, 0xc000
	s_addc_u32 s11, s9, 0
	s_add_u32 s12, s10, 0xc000
	s_addc_u32 s13, s11, 0
	s_add_u32 s54, s12, 0xc000
	s_addc_u32 s55, s13, 0
	global_load_dwordx4 v[2:5], v130, s[0:1]
	global_load_dwordx4 v[6:9], v130, s[2:3]
	global_load_dwordx4 v[10:13], v130, s[4:5]
	global_load_dwordx4 v[14:17], v130, s[6:7]
	global_load_dwordx4 v[18:21], v134, s[8:9]
	global_load_dwordx4 v[22:25], v134, s[10:11]
	global_load_dwordx4 v[26:29], v134, s[12:13]
	global_load_dwordx4 v[30:33], v134, s[54:55]
	s_waitcnt lgkmcnt(0)
	s_barrier
	s_waitcnt vmcnt(24)
	ds_write_b128 v138, v[34:37]
	ds_write_b128 v138, v[38:41] offset:4608
	ds_write_b128 v138, v[42:45] offset:9216
	ds_write_b128 v138, v[46:49] offset:13824
	ds_write_b128 v139, v[50:53]
	ds_write_b128 v139, v[54:57] offset:4608
	ds_write_b128 v139, v[58:61] offset:9216
	ds_write_b128 v139, v[62:65] offset:13824
	global_load_dwordx4 v[34:37], v130, s[0:1] offset:128
	global_load_dwordx4 v[38:41], v130, s[2:3] offset:128
	global_load_dwordx4 v[42:45], v130, s[4:5] offset:128
	global_load_dwordx4 v[46:49], v130, s[6:7] offset:128
	global_load_dwordx4 v[50:53], v134, s[8:9] offset:128
	global_load_dwordx4 v[54:57], v134, s[10:11] offset:128
	global_load_dwordx4 v[58:61], v134, s[12:13] offset:128
	global_load_dwordx4 v[62:65], v134, s[54:55] offset:128
	s_waitcnt lgkmcnt(0)
	s_barrier
	s_waitcnt vmcnt(24)
	ds_write_b128 v138, v[66:69] offset:18432
	ds_write_b128 v138, v[70:73] offset:23040
	ds_write_b128 v138, v[74:77] offset:27648
	ds_write_b128 v138, v[78:81] offset:32256
	ds_write_b128 v139, v[82:85] offset:18432
	ds_write_b128 v139, v[86:89] offset:23040
	ds_write_b128 v139, v[90:93] offset:27648
	ds_write_b128 v139, v[94:97] offset:32256
	global_load_dwordx4 v[66:69], v130, s[0:1] offset:256
	global_load_dwordx4 v[70:73], v130, s[2:3] offset:256
	global_load_dwordx4 v[74:77], v130, s[4:5] offset:256
	global_load_dwordx4 v[78:81], v130, s[6:7] offset:256
	global_load_dwordx4 v[82:85], v134, s[8:9] offset:256
	global_load_dwordx4 v[86:89], v134, s[10:11] offset:256
	global_load_dwordx4 v[90:93], v134, s[12:13] offset:256
	global_load_dwordx4 v[94:97], v134, s[54:55] offset:256
	s_waitcnt lgkmcnt(0)
	s_barrier
	s_waitcnt vmcnt(24)
	ds_write_b128 v138, v[98:101] offset:36864
	ds_write_b128 v138, v[102:105] offset:41472
	ds_write_b128 v138, v[106:109] offset:46080
	ds_write_b128 v138, v[110:113] offset:50688
	ds_write_b128 v139, v[114:117] offset:36864
	ds_write_b128 v139, v[118:121] offset:41472
	ds_write_b128 v139, v[122:125] offset:46080
	ds_write_b128 v139, v[126:129] offset:50688
	global_load_dwordx4 v[98:101], v130, s[0:1] offset:384
	global_load_dwordx4 v[102:105], v130, s[2:3] offset:384
	global_load_dwordx4 v[106:109], v130, s[4:5] offset:384
	global_load_dwordx4 v[110:113], v130, s[6:7] offset:384
	global_load_dwordx4 v[114:117], v134, s[8:9] offset:384
	global_load_dwordx4 v[118:121], v134, s[10:11] offset:384
	global_load_dwordx4 v[122:125], v134, s[12:13] offset:384
	global_load_dwordx4 v[126:129], v134, s[54:55] offset:384
	s_waitcnt lgkmcnt(0)
	s_barrier
	s_waitcnt vmcnt(24)
	ds_write_b128 v138, v[2:5]
	ds_write_b128 v138, v[6:9] offset:4608
	ds_write_b128 v138, v[10:13] offset:9216
	ds_write_b128 v138, v[14:17] offset:13824
	ds_write_b128 v139, v[18:21]
	ds_write_b128 v139, v[22:25] offset:4608
	ds_write_b128 v139, v[26:29] offset:9216
	ds_write_b128 v139, v[30:33] offset:13824
	global_load_dwordx4 v[2:5], v130, s[0:1] offset:512
	global_load_dwordx4 v[6:9], v130, s[2:3] offset:512
	global_load_dwordx4 v[10:13], v130, s[4:5] offset:512
	global_load_dwordx4 v[14:17], v130, s[6:7] offset:512
	global_load_dwordx4 v[18:21], v134, s[8:9] offset:512
	global_load_dwordx4 v[22:25], v134, s[10:11] offset:512
	global_load_dwordx4 v[26:29], v134, s[12:13] offset:512
	global_load_dwordx4 v[30:33], v134, s[54:55] offset:512
	s_waitcnt lgkmcnt(0)
	s_barrier
	s_waitcnt vmcnt(24)
	ds_write_b128 v138, v[34:37] offset:18432
	ds_write_b128 v138, v[38:41] offset:23040
	ds_write_b128 v138, v[42:45] offset:27648
	ds_write_b128 v138, v[46:49] offset:32256
	ds_write_b128 v139, v[50:53] offset:18432
	ds_write_b128 v139, v[54:57] offset:23040
	ds_write_b128 v139, v[58:61] offset:27648
	ds_write_b128 v139, v[62:65] offset:32256
	global_load_dwordx4 v[34:37], v130, s[0:1] offset:640
	global_load_dwordx4 v[38:41], v130, s[2:3] offset:640
	global_load_dwordx4 v[42:45], v130, s[4:5] offset:640
	global_load_dwordx4 v[46:49], v130, s[6:7] offset:640
	global_load_dwordx4 v[50:53], v134, s[8:9] offset:640
	global_load_dwordx4 v[54:57], v134, s[10:11] offset:640
	global_load_dwordx4 v[58:61], v134, s[12:13] offset:640
	global_load_dwordx4 v[62:65], v134, s[54:55] offset:640
	s_waitcnt lgkmcnt(0)
	s_barrier
	s_add_i32 s31, s31, s30
	s_mov_b32 s58, s60
	s_mov_b32 s59, s61
	s_cmpk_lt_i32 s31, 0x400
	s_cbranch_scc1 .Lmrgp_task
	s_branch .Lmrg_done
.Lmrg_done:
.LBB0_2270:
	s_waitcnt vmcnt(0)
	v_mov_b32_e32 v0, v224
	s_barrier
	s_nop 0
	v_cmp_eq_u32_e32 vcc, 0, v0
	s_and_saveexec_b64 s[0:1], vcc
	s_cbranch_execz .LBB0_2322
	s_getreg_b32 s2, hwreg(HW_REG_XCC_ID, 0, 4)
	s_waitcnt vmcnt(0) expcnt(0) lgkmcnt(0)
	ds_read_b32 v3, v233
	ds_read_b32 v2, v238
	s_and_b32 s31, s2, 15
	s_waitcnt lgkmcnt(1)
	v_cmp_ne_u32_e32 vcc, 0, v3
	s_cbranch_vccnz .LBB0_2286
	s_mov_b32 s52, 1
	s_branch .LBB0_2274
